# v62 + G4 split epilogue: the 8 SwiGLU (ai,m) blocks of a unit with a successor spread over its last load segment and the next unit's first two (3/2/3), no aligned epilogue stop
# baseline (speedup 1.0000x reference)
;     __host__ __device__ bool next(int i_, Unit& u) const {
;         const int i = i_ + i0; if (i >= i1) return false;
;         const long L = (long)i * G + c; if (L >= nwg) return false;
;         int wgid = (int)L; { const int q = nwg / NXCD, r = nwg % NXCD, xcd = wgid % NXCD, off = wgid / NXCD; wgid = (xcd < r ? xcd * (q + 1) : r * (q + 1) + (xcd - r) * q) + off; }
;         const int nig = WGM * nN, gid = wgid / nig, fm = gid * WGM, gsz = (nM - fm) < WGM ? (nM - fm) : WGM;
;         u.pm = fm + ((wgid % nig) % gsz); u.pn = (wgid % nig) / gsz; return true;
; template <class Epi, class Sched, bool ALIGN_EPI = false, bool SP2 = false, bool KHOOK = false>
; __device__ __forceinline__ void gemm_phase(PG8_LAS unsigned char* lds, const Gemm g, const Sched& S, const Epi& E, const int tid_in) {
;     ...
;         const bool has_next = S.next(ui + 1, nxt);
;         const char* nA = has_next ? (const char*)g.A + (size_t)nxt.pm * tstep + (size_t)nxt.pn * ksl : cA; const char* nB = has_next ? (const char*)g.Bt + (size_t)nxt.pn * bts + (size_t)nxt.pn * ksl + (gdv ? (size_t)(nxt.pm / gdv) * gst : 0) : cB;
.LBB0_1059:
	s_add_i32 s42, s42, 1
	s_cmp_eq_u32 s42, 0x7fffffff
	s_mov_b64 s[14:15], 0
	s_cbranch_scc1 .LBB0_1062
	s_mul_i32 s11, s42, s66
	s_mul_hi_u32 s13, s42, s94
	s_add_i32 s13, s13, s11
	s_mul_i32 s11, s42, s94
	s_add_u32 s16, s11, s92
	s_addc_u32 s17, s13, s80
	v_mov_b64_e32 v[226:227], 0x57f
	v_cmp_gt_i64_e32 vcc, s[16:17], v[226:227]
	s_cbranch_vccnz .LBB0_1062
	s_ashr_i32 s10, s16, 31
	s_lshr_b32 s10, s10, 29
	s_add_i32 s10, s16, s10
	s_ashr_i32 s11, s10, 3
	s_and_b32 s10, s10, -8
	s_sub_i32 s10, s16, s10
	s_cmp_lt_i32 s10, 0
	s_movk_i32 s12, 0xb1
	s_cselect_b32 s12, s12, 0xb0
	s_mul_i32 s10, s10, s12
	s_add_i32 s10, s10, s11
	s_mul_hi_i32 s11, s10, 0x2e8ba2e9
	s_lshr_b32 s12, s11, 31
	s_ashr_i32 s11, s11, 5
	s_add_i32 s11, s11, s12
	s_lshl_b32 s12, s11, 2
	s_sub_i32 s13, 32, s12
	s_min_i32 s13, s13, 4
	s_abs_i32 s14, s13
	v_cvt_f32_u32_e32 v226, s14
	s_sub_i32 s16, 0, s14
	s_mulk_i32 s11, 0xb0
	s_sub_i32 s11, s10, s11
	v_rcp_iflag_f32_e32 v226, v226
	s_abs_i32 s10, s11
	s_xor_b32 s15, s11, s13
	s_ashr_i32 s15, s15, 31
	v_mul_f32_e32 v226, 0x4f7ffffe, v226
	v_cvt_u32_f32_e32 v226, v226
	s_nop 0
	v_readfirstlane_b32 s17, v226
	s_mul_i32 s16, s16, s17
	s_mul_hi_u32 s16, s17, s16
	s_add_i32 s17, s17, s16
	s_mul_hi_u32 s16, s10, s17
	s_mul_i32 s17, s16, s14
	s_sub_i32 s10, s10, s17
	s_add_i32 s22, s16, 1
	s_sub_i32 s17, s10, s14
	s_cmp_ge_u32 s10, s14
	s_cselect_b32 s16, s22, s16
	s_cselect_b32 s10, s17, s10
	s_add_i32 s17, s16, 1
	s_cmp_ge_u32 s10, s14
	s_cselect_b32 s10, s17, s16
	s_xor_b32 s10, s10, s15
	s_sub_i32 s10, s10, s15
	s_mul_i32 s13, s10, s13
	s_sub_i32 s11, s11, s13
	s_add_i32 s12, s12, s11
	s_mov_b64 s[14:15], -1

; __device__ __forceinline__ unsigned cvt_pk_bf16(float lo, float hi) { const f32x2_t v = {lo, hi}; const bf16x2_t c = __builtin_convertvector(v, bf16x2_t); return __builtin_bit_cast(unsigned, c); }
; __device__ __forceinline__ float siluf_fast(float x) { return x * sigmoidf_fast(x); }
; #define PG8_STAGE(bufoff, gbase, voff) do { _Pragma("unroll") for (int _i = 0; _i < 2; ++_i) \
;         __builtin_amdgcn_global_load_lds((const unsigned*)((const char*)(gbase) + (voff)[_i]), (PG8_LAS unsigned*)(lds + (bufoff) + ldsw + _i * 8192), 16, 0, 0); } while (0)
; #define PG8_LDA(dst, b, h) do { _Pragma("unroll") for (int m = 0; m < 4; ++m) _Pragma("unroll") for (int k = 0; k < 2; ++k) dst[m][k] = *(const PG8_LAS bf16x8*)(lds + PG8_SA(b, h) + aoff + m * 2048 + k * 1024); } while (0)
; #define PG8_BAR __builtin_amdgcn_s_barrier()
;     __device__ __forceinline__ void operator()(const f32x4 (&acc)[2][2][4][2], const Unit& u, int wr, int wc, int fr, int fq) const {
;         const int row0 = u.pm * BM + wr * 64 + fr, col0 = u.pn * HALF + wc * 32 + 8 * fq;
; #pragma unroll
;         for (int ai = 0; ai < 2; ++ai)
; #pragma unroll
;             for (int m = 0; m < 4; ++m) { const size_t r = (size_t)(row0 + ai * HALF + m * 16);
;                 const f32x4 g0 = acc[ai][0][m][0], u0 = acc[ai][0][m][1], g1 = acc[ai][1][m][0], u1 = acc[ai][1][m][1];
;                 u32x4 w; w.x = cvt_pk_bf16(siluf_fast(g0[0]) * u0[0], siluf_fast(g0[1]) * u0[1]); w.y = cvt_pk_bf16(siluf_fast(g0[2]) * u0[2], siluf_fast(g0[3]) * u0[3]);
;                 w.z = cvt_pk_bf16(siluf_fast(g1[0]) * u1[0], siluf_fast(g1[1]) * u1[1]); w.w = cvt_pk_bf16(siluf_fast(g1[2]) * u1[2], siluf_fast(g1[3]) * u1[3]);
;                 *(u32x4*)(O + r * ldo + col0) = w; }
; template <class Epi, class Sched, bool ALIGN_EPI = false, bool SP2 = false, bool KHOOK = false>
; __device__ __forceinline__ void gemm_phase(PG8_LAS unsigned char* lds, const Gemm g, const Sched& S, const Epi& E, const int tid_in) {
;     ...
;             PG8_LDB(B0, 0, 0); PG8_LDB(B1, 0, 1); PG8_SCHED; PG8_LDA(At, 0, 0); PG8_STAGE(PG8_SA(1, 1), a1 + hstep, voffA);
;             PG8_WAIT_V(8); PG8_WAIT_L(0); PG8_BAR; PG8_MMA(0, 0, At, B0); PG8_MMA(0, 1, At, B1); PG8_BAR; PG8_SCHED;
;             PG8_LDA(At, 0, 1); PG8_STAGE(PG8_SB(0, 0), b2, voffB); PG8_STAGE(PG8_SB(0, 1), b2 + hstep, voffB); PG8_STAGE(PG8_SA(0, 0), a2, voffA);
.Lg4_peel_e1:
	s_add_u32 s30, s26, 0xfff80080
	s_addc_u32 s31, s27, -1
	s_add_i32 s47, 0, 0x10000
	s_cmp_eq_u32 s46, 28
	s_cselect_b32 s49, s13, s31
	s_cselect_b32 s48, s24, s30
	s_cselect_b32 s31, s11, s45
	s_cselect_b32 s30, s25, s44
	s_add_i32 s52, 0, 0x14000
	v_add_u32_e32 v152, s47, v137
	v_add_u32_e32 v168, s52, v137
	ds_read_b128 v[140:143], v152
	ds_read_b128 v[144:147], v152 offset:1024
	ds_read_b128 v[148:151], v152 offset:2048
	ds_read_b128 v[152:155], v152 offset:3072
	ds_read_b128 v[156:159], v168
	ds_read_b128 v[160:163], v168 offset:1024
	ds_read_b128 v[164:167], v168 offset:2048
	ds_read_b128 v[168:171], v168 offset:3072
	v_lshl_add_u64 v[192:193], s[26:27], 0, v[132:133]
	s_add_i32 m0, s36, 0xc000
	ds_read_b128 v[172:175], v139
	ds_read_b128 v[176:179], v139 offset:1024
	ds_read_b128 v[180:183], v139 offset:2048
	ds_read_b128 v[184:187], v139 offset:3072
	ds_read_b128 v[188:191], v139 offset:4096
	ds_read_b128 v[198:201], v139 offset:5120
	ds_read_b128 v[202:205], v139 offset:6144
	ds_read_b128 v[206:209], v139 offset:7168
	global_load_lds_dwordx4 v[192:193], off
	v_lshl_add_u64 v[192:193], s[26:27], 0, v[134:135]
	s_add_i32 m0, s36, 0xe000
	s_nop 0
	global_load_lds_dwordx4 v[192:193], off
	s_mov_b32 s56, 0x2c000
	s_mov_b32 s57, 0
	s_mov_b32 s58, 0xdc000
	s_mov_b32 s59, 0
	v_lshl_add_u64 v[248:249], v[248:249], 0, s[56:57]
	v_mul_f32_e32 v218, 0xbfb8aa3b, v78
	v_mul_f32_e32 v219, 0xbfb8aa3b, v79
	v_mul_f32_e32 v220, 0xbfb8aa3b, v80
	v_mul_f32_e32 v221, 0xbfb8aa3b, v81
	v_exp_f32_e32 v218, v218
	v_exp_f32_e32 v219, v219
	v_exp_f32_e32 v220, v220
	v_exp_f32_e32 v221, v221
	v_add_f32_e32 v218, 1.0, v218
	v_add_f32_e32 v219, 1.0, v219
	v_add_f32_e32 v220, 1.0, v220
	v_add_f32_e32 v221, 1.0, v221
	v_rcp_f32_e32 v218, v218
	v_rcp_f32_e32 v219, v219
	v_rcp_f32_e32 v220, v220
	v_rcp_f32_e32 v221, v221
	v_mul_f32_e32 v78, v78, v218
	v_mul_f32_e32 v79, v79, v219
	v_mul_f32_e32 v80, v80, v220
	v_mul_f32_e32 v81, v81, v221
	v_mul_f32_e32 v74, v74, v78
	v_mul_f32_e32 v75, v75, v79
	v_mul_f32_e32 v76, v76, v80
	v_mul_f32_e32 v77, v77, v81
	v_mul_f32_e32 v218, 0xbfb8aa3b, v70
	v_mul_f32_e32 v219, 0xbfb8aa3b, v71
	v_mul_f32_e32 v220, 0xbfb8aa3b, v72
	v_mul_f32_e32 v221, 0xbfb8aa3b, v73
	v_exp_f32_e32 v218, v218
	v_exp_f32_e32 v219, v219
	v_exp_f32_e32 v220, v220
	v_exp_f32_e32 v221, v221
	v_add_f32_e32 v218, 1.0, v218
	v_add_f32_e32 v219, 1.0, v219
	v_add_f32_e32 v220, 1.0, v220
	v_add_f32_e32 v221, 1.0, v221
	v_rcp_f32_e32 v218, v218
	v_rcp_f32_e32 v219, v219
	v_rcp_f32_e32 v220, v220
	v_rcp_f32_e32 v221, v221
	v_mul_f32_e32 v70, v70, v218
	v_mul_f32_e32 v71, v71, v219
	v_mul_f32_e32 v72, v72, v220
	v_mul_f32_e32 v73, v73, v221
	v_mul_f32_e32 v66, v66, v70
	v_mul_f32_e32 v67, v67, v71
	v_mul_f32_e32 v68, v68, v72
	v_mul_f32_e32 v69, v69, v73
	v_cvt_pk_bf16_f32 v74, v74, v75
	v_cvt_pk_bf16_f32 v75, v76, v77
	v_cvt_pk_bf16_f32 v76, v66, v67
	v_cvt_pk_bf16_f32 v77, v68, v69
	global_store_dwordx4 v[248:249], v[74:77], off
	v_lshl_add_u64 v[248:249], v[248:249], 0, s[58:59]
	v_mul_f32_e32 v218, 0xbfb8aa3b, v62
	v_mul_f32_e32 v219, 0xbfb8aa3b, v63
	v_mul_f32_e32 v220, 0xbfb8aa3b, v64
	v_mul_f32_e32 v221, 0xbfb8aa3b, v65
	v_exp_f32_e32 v218, v218
	v_exp_f32_e32 v219, v219
	v_exp_f32_e32 v220, v220
	v_exp_f32_e32 v221, v221
	v_add_f32_e32 v218, 1.0, v218
	v_add_f32_e32 v219, 1.0, v219
	v_add_f32_e32 v220, 1.0, v220
	v_add_f32_e32 v221, 1.0, v221
	v_rcp_f32_e32 v218, v218
	v_rcp_f32_e32 v219, v219
	v_rcp_f32_e32 v220, v220
	v_rcp_f32_e32 v221, v221
	v_mul_f32_e32 v62, v62, v218
	v_mul_f32_e32 v63, v63, v219
	v_mul_f32_e32 v64, v64, v220
	v_mul_f32_e32 v65, v65, v221
	v_mul_f32_e32 v58, v58, v62
	v_mul_f32_e32 v59, v59, v63
	v_mul_f32_e32 v60, v60, v64
	v_mul_f32_e32 v61, v61, v65
	v_mul_f32_e32 v218, 0xbfb8aa3b, v54
	v_mul_f32_e32 v219, 0xbfb8aa3b, v55
	v_mul_f32_e32 v220, 0xbfb8aa3b, v56
	v_mul_f32_e32 v221, 0xbfb8aa3b, v57
	v_exp_f32_e32 v218, v218
	v_exp_f32_e32 v219, v219
	v_exp_f32_e32 v220, v220
	v_exp_f32_e32 v221, v221
	v_add_f32_e32 v218, 1.0, v218
	v_add_f32_e32 v219, 1.0, v219
	v_add_f32_e32 v220, 1.0, v220
	v_add_f32_e32 v221, 1.0, v221
	v_rcp_f32_e32 v218, v218
	v_rcp_f32_e32 v219, v219
	v_rcp_f32_e32 v220, v220
	v_rcp_f32_e32 v221, v221
	v_mul_f32_e32 v54, v54, v218
	v_mul_f32_e32 v55, v55, v219
	v_mul_f32_e32 v56, v56, v220
	v_mul_f32_e32 v57, v57, v221
	v_mul_f32_e32 v50, v50, v54
	v_mul_f32_e32 v51, v51, v55
	v_mul_f32_e32 v52, v52, v56
	v_mul_f32_e32 v53, v53, v57
	v_cvt_pk_bf16_f32 v58, v58, v59
	v_cvt_pk_bf16_f32 v59, v60, v61
	v_cvt_pk_bf16_f32 v60, v50, v51
	v_cvt_pk_bf16_f32 v61, v52, v53
	global_store_dwordx4 v[248:249], v[58:61], off
	s_waitcnt vmcnt(13)
	s_waitcnt lgkmcnt(0)
	s_barrier
; __device__ __forceinline__ unsigned cvt_pk_bf16(float lo, float hi) { const f32x2_t v = {lo, hi}; const bf16x2_t c = __builtin_convertvector(v, bf16x2_t); return __builtin_bit_cast(unsigned, c); }
; __device__ __forceinline__ float siluf_fast(float x) { return x * sigmoidf_fast(x); }
; #define PG8_STAGE(bufoff, gbase, voff) do { _Pragma("unroll") for (int _i = 0; _i < 2; ++_i) \
;         __builtin_amdgcn_global_load_lds((const unsigned*)((const char*)(gbase) + (voff)[_i]), (PG8_LAS unsigned*)(lds + (bufoff) + ldsw + _i * 8192), 16, 0, 0); } while (0)
; #define PG8_LDA(dst, b, h) do { _Pragma("unroll") for (int m = 0; m < 4; ++m) _Pragma("unroll") for (int k = 0; k < 2; ++k) dst[m][k] = *(const PG8_LAS bf16x8*)(lds + PG8_SA(b, h) + aoff + m * 2048 + k * 1024); } while (0)
; #define PG8_WAIT_V(n) asm volatile("s_waitcnt vmcnt(" #n ")" ::: "memory")
; #define PG8_WAIT_L(n) asm volatile("s_waitcnt lgkmcnt(" #n ")" ::: "memory")
; #define PG8_BAR __builtin_amdgcn_s_barrier()
; #define PG8_SCHED __builtin_amdgcn_sched_barrier(0)
;     __device__ __forceinline__ void operator()(const f32x4 (&acc)[2][2][4][2], const Unit& u, int wr, int wc, int fr, int fq) const {
;     ...
;             for (int m = 0; m < 4; ++m) { const size_t r = (size_t)(row0 + ai * HALF + m * 16);
;                 const f32x4 g0 = acc[ai][0][m][0], u0 = acc[ai][0][m][1], g1 = acc[ai][1][m][0], u1 = acc[ai][1][m][1];
;                 u32x4 w; w.x = cvt_pk_bf16(siluf_fast(g0[0]) * u0[0], siluf_fast(g0[1]) * u0[1]); w.y = cvt_pk_bf16(siluf_fast(g0[2]) * u0[2], siluf_fast(g0[3]) * u0[3]);
;                 w.z = cvt_pk_bf16(siluf_fast(g1[0]) * u1[0], siluf_fast(g1[1]) * u1[1]); w.w = cvt_pk_bf16(siluf_fast(g1[2]) * u1[2], siluf_fast(g1[3]) * u1[3]);
;                 *(u32x4*)(O + r * ldo + col0) = w; }
; template <class Epi, class Sched, bool ALIGN_EPI = false, bool SP2 = false, bool KHOOK = false>
; __device__ __forceinline__ void gemm_phase(PG8_LAS unsigned char* lds, const Gemm g, const Sched& S, const Epi& E, const int tid_in) {
;     ...
;             PG8_WAIT_V(8); PG8_WAIT_L(0); PG8_BAR; PG8_MMA(0, 0, At, B0); PG8_MMA(0, 1, At, B1); PG8_BAR; PG8_SCHED;
;             PG8_LDA(At, 0, 1); PG8_STAGE(PG8_SB(0, 0), b2, voffB); PG8_STAGE(PG8_SB(0, 1), b2 + hstep, voffB); PG8_STAGE(PG8_SA(0, 0), a2, voffA);
	s_setprio 1
	s_waitcnt lgkmcnt(0)
	v_mfma_f32_16x16x32_bf16 v[126:129], v[140:143], v[172:175], 0
	v_mfma_f32_16x16x32_bf16 v[122:125], v[148:151], v[172:175], 0
	v_mfma_f32_16x16x32_bf16 v[110:113], v[140:143], v[180:183], 0
	v_mfma_f32_16x16x32_bf16 v[106:109], v[148:151], v[180:183], 0
	v_mfma_f32_16x16x32_bf16 v[94:97], v[140:143], v[188:191], 0
	v_mfma_f32_16x16x32_bf16 v[90:93], v[148:151], v[188:191], 0
	v_mfma_f32_16x16x32_bf16 v[78:81], v[140:143], v[202:205], 0
	v_mfma_f32_16x16x32_bf16 v[74:77], v[148:151], v[202:205], 0
	v_mfma_f32_16x16x32_bf16 v[126:129], v[144:147], v[176:179], v[126:129]
	v_mfma_f32_16x16x32_bf16 v[122:125], v[152:155], v[176:179], v[122:125]
	v_mfma_f32_16x16x32_bf16 v[110:113], v[144:147], v[184:187], v[110:113]
	v_mfma_f32_16x16x32_bf16 v[106:109], v[152:155], v[184:187], v[106:109]
	v_mfma_f32_16x16x32_bf16 v[94:97], v[144:147], v[198:201], v[94:97]
	v_mfma_f32_16x16x32_bf16 v[90:93], v[152:155], v[198:201], v[90:93]
	v_mfma_f32_16x16x32_bf16 v[78:81], v[144:147], v[206:209], v[78:81]
	v_mfma_f32_16x16x32_bf16 v[74:77], v[152:155], v[206:209], v[74:77]
	s_setprio 0
	s_setprio 1
	v_mfma_f32_16x16x32_bf16 v[118:121], v[156:159], v[172:175], 0
	v_mfma_f32_16x16x32_bf16 v[114:117], v[164:167], v[172:175], 0
	v_mfma_f32_16x16x32_bf16 v[102:105], v[156:159], v[180:183], 0
	v_mfma_f32_16x16x32_bf16 v[98:101], v[164:167], v[180:183], 0
	v_mfma_f32_16x16x32_bf16 v[86:89], v[156:159], v[188:191], 0
	v_mfma_f32_16x16x32_bf16 v[82:85], v[164:167], v[188:191], 0
	v_mfma_f32_16x16x32_bf16 v[70:73], v[156:159], v[202:205], 0
	v_mfma_f32_16x16x32_bf16 v[66:69], v[164:167], v[202:205], 0
	v_mfma_f32_16x16x32_bf16 v[118:121], v[160:163], v[176:179], v[118:121]
	v_mfma_f32_16x16x32_bf16 v[114:117], v[168:171], v[176:179], v[114:117]
	v_mfma_f32_16x16x32_bf16 v[102:105], v[160:163], v[184:187], v[102:105]
	v_mfma_f32_16x16x32_bf16 v[98:101], v[168:171], v[184:187], v[98:101]
	v_mfma_f32_16x16x32_bf16 v[86:89], v[160:163], v[198:201], v[86:89]
	v_mfma_f32_16x16x32_bf16 v[82:85], v[168:171], v[198:201], v[82:85]
	v_mfma_f32_16x16x32_bf16 v[70:73], v[160:163], v[206:209], v[70:73]
	v_mfma_f32_16x16x32_bf16 v[66:69], v[168:171], v[206:209], v[66:69]
	s_setprio 0
	s_barrier
	s_add_i32 s47, s47, s33
	v_lshl_add_u64 v[192:193], s[30:31], 0, v[32:33]
	s_mov_b32 m0, s47
	ds_read_b128 v[172:175], v139 offset:16384
	ds_read_b128 v[176:179], v139 offset:17408
	ds_read_b128 v[180:183], v139 offset:18432
	ds_read_b128 v[184:187], v139 offset:19456
	ds_read_b128 v[188:191], v139 offset:20480
	ds_read_b128 v[198:201], v139 offset:21504
	ds_read_b128 v[202:205], v139 offset:22528
	ds_read_b128 v[206:209], v139 offset:23552
	global_load_lds_dwordx4 v[192:193], off
	s_add_i32 m0, s47, 0x2000
	s_add_u32 s50, s30, 0x80000
	v_lshl_add_u64 v[210:211], s[30:31], 0, v[130:131]
	s_addc_u32 s51, s31, 0
	s_add_i32 s47, s52, s33
	global_load_lds_dwordx4 v[210:211], off
	v_lshl_add_u64 v[212:213], s[50:51], 0, v[32:33]
	s_mov_b32 m0, s47
	v_lshl_add_u64 v[214:215], s[48:49], 0, v[130:131]
	global_load_lds_dwordx4 v[212:213], off
	v_lshl_add_u64 v[212:213], s[50:51], 0, v[130:131]
	s_add_i32 m0, s47, 0x2000
	s_nop 0
	global_load_lds_dwordx4 v[212:213], off
	v_lshl_add_u64 v[212:213], s[48:49], 0, v[32:33]
	s_mov_b32 m0, s36
	s_nop 0
	global_load_lds_dwordx4 v[212:213], off
	s_mov_b32 m0, s37
	s_nop 0
	global_load_lds_dwordx4 v[214:215], off
	s_mov_b32 s56, 0x2c000
	s_mov_b32 s57, 0
	s_mov_b32 s58, 0xdc000
	s_mov_b32 s59, 0
	v_lshl_add_u64 v[248:249], v[248:249], 0, s[56:57]
	v_mul_f32_e32 v218, 0xbfb8aa3b, v46
	v_mul_f32_e32 v219, 0xbfb8aa3b, v47
	v_mul_f32_e32 v220, 0xbfb8aa3b, v48
	v_mul_f32_e32 v221, 0xbfb8aa3b, v49
	v_exp_f32_e32 v218, v218
	v_exp_f32_e32 v219, v219
	v_exp_f32_e32 v220, v220
	v_exp_f32_e32 v221, v221
	v_add_f32_e32 v218, 1.0, v218
	v_add_f32_e32 v219, 1.0, v219
	v_add_f32_e32 v220, 1.0, v220
	v_add_f32_e32 v221, 1.0, v221
	v_rcp_f32_e32 v218, v218
	v_rcp_f32_e32 v219, v219
	v_rcp_f32_e32 v220, v220
	v_rcp_f32_e32 v221, v221
	v_mul_f32_e32 v46, v46, v218
	v_mul_f32_e32 v47, v47, v219
	v_mul_f32_e32 v48, v48, v220
	v_mul_f32_e32 v49, v49, v221
	v_mul_f32_e32 v42, v42, v46
	v_mul_f32_e32 v43, v43, v47
	v_mul_f32_e32 v44, v44, v48
	v_mul_f32_e32 v45, v45, v49
	v_mul_f32_e32 v218, 0xbfb8aa3b, v38
	v_mul_f32_e32 v219, 0xbfb8aa3b, v39
	v_mul_f32_e32 v220, 0xbfb8aa3b, v40
	v_mul_f32_e32 v221, 0xbfb8aa3b, v41
	v_exp_f32_e32 v218, v218
	v_exp_f32_e32 v219, v219
	v_exp_f32_e32 v220, v220
	v_exp_f32_e32 v221, v221
	v_add_f32_e32 v218, 1.0, v218
	v_add_f32_e32 v219, 1.0, v219
	v_add_f32_e32 v220, 1.0, v220
	v_add_f32_e32 v221, 1.0, v221
	v_rcp_f32_e32 v218, v218
	v_rcp_f32_e32 v219, v219
	v_rcp_f32_e32 v220, v220
	v_rcp_f32_e32 v221, v221
	v_mul_f32_e32 v38, v38, v218
	v_mul_f32_e32 v39, v39, v219
	v_mul_f32_e32 v40, v40, v220
	v_mul_f32_e32 v41, v41, v221
	v_mul_f32_e32 v34, v34, v38
	v_mul_f32_e32 v35, v35, v39
	v_mul_f32_e32 v36, v36, v40
	v_mul_f32_e32 v37, v37, v41
	v_cvt_pk_bf16_f32 v42, v42, v43
	v_cvt_pk_bf16_f32 v43, v44, v45
	v_cvt_pk_bf16_f32 v44, v34, v35
	v_cvt_pk_bf16_f32 v45, v36, v37
	global_store_dwordx4 v[248:249], v[42:45], off
	v_lshl_add_u64 v[248:249], v[248:249], 0, s[56:57]
	v_mul_f32_e32 v218, 0xbfb8aa3b, v28
	v_mul_f32_e32 v219, 0xbfb8aa3b, v29
	v_mul_f32_e32 v220, 0xbfb8aa3b, v30
	v_mul_f32_e32 v221, 0xbfb8aa3b, v31
	v_exp_f32_e32 v218, v218
	v_exp_f32_e32 v219, v219
	v_exp_f32_e32 v220, v220
	v_exp_f32_e32 v221, v221
	v_add_f32_e32 v218, 1.0, v218
	v_add_f32_e32 v219, 1.0, v219
	v_add_f32_e32 v220, 1.0, v220
	v_add_f32_e32 v221, 1.0, v221
	v_rcp_f32_e32 v218, v218
	v_rcp_f32_e32 v219, v219
	v_rcp_f32_e32 v220, v220
; __device__ __forceinline__ unsigned cvt_pk_bf16(float lo, float hi) { const f32x2_t v = {lo, hi}; const bf16x2_t c = __builtin_convertvector(v, bf16x2_t); return __builtin_bit_cast(unsigned, c); }
; __device__ __forceinline__ float siluf_fast(float x) { return x * sigmoidf_fast(x); }
; #define PG8_STAGE(bufoff, gbase, voff) do { _Pragma("unroll") for (int _i = 0; _i < 2; ++_i) \
;         __builtin_amdgcn_global_load_lds((const unsigned*)((const char*)(gbase) + (voff)[_i]), (PG8_LAS unsigned*)(lds + (bufoff) + ldsw + _i * 8192), 16, 0, 0); } while (0)
; #define PG8_LDA(dst, b, h) do { _Pragma("unroll") for (int m = 0; m < 4; ++m) _Pragma("unroll") for (int k = 0; k < 2; ++k) dst[m][k] = *(const PG8_LAS bf16x8*)(lds + PG8_SA(b, h) + aoff + m * 2048 + k * 1024); } while (0)
; #define PG8_LDB(dst, b, h) do { _Pragma("unroll") for (int n = 0; n < 2; ++n) _Pragma("unroll") for (int k = 0; k < 2; ++k) dst[n][k] = *(const PG8_LAS bf16x8*)(lds + PG8_SB(b, h) + boff + n * 2048 + k * 1024); } while (0)
;     __device__ __forceinline__ void operator()(const f32x4 (&acc)[2][2][4][2], const Unit& u, int wr, int wc, int fr, int fq) const {
;     ...
;             for (int m = 0; m < 4; ++m) { const size_t r = (size_t)(row0 + ai * HALF + m * 16);
;                 const f32x4 g0 = acc[ai][0][m][0], u0 = acc[ai][0][m][1], g1 = acc[ai][1][m][0], u1 = acc[ai][1][m][1];
;                 u32x4 w; w.x = cvt_pk_bf16(siluf_fast(g0[0]) * u0[0], siluf_fast(g0[1]) * u0[1]); w.y = cvt_pk_bf16(siluf_fast(g0[2]) * u0[2], siluf_fast(g0[3]) * u0[3]);
;                 w.z = cvt_pk_bf16(siluf_fast(g1[0]) * u1[0], siluf_fast(g1[1]) * u1[1]); w.w = cvt_pk_bf16(siluf_fast(g1[2]) * u1[2], siluf_fast(g1[3]) * u1[3]);
;                 *(u32x4*)(O + r * ldo + col0) = w; }
; template <class Epi, class Sched, bool ALIGN_EPI = false, bool SP2 = false, bool KHOOK = false>
; __device__ __forceinline__ void gemm_phase(PG8_LAS unsigned char* lds, const Gemm g, const Sched& S, const Epi& E, const int tid_in) {
;     ...
;             PG8_WAIT_V(8); PG8_WAIT_L(0); PG8_BAR; PG8_MMA(1, 0, At, B0); PG8_MMA(1, 1, At, B1); PG8_BAR; PG8_SCHED;
;             PG8_LDB(B0, 1, 0); PG8_LDB(B1, 1, 1); PG8_SCHED; PG8_LDA(At, 1, 0); PG8_STAGE(PG8_SA(0, 1), a2 + hstep, voffA);
;             PG8_WAIT_V(8); PG8_WAIT_L(0); PG8_BAR; PG8_MMA(0, 0, At, B0); PG8_MMA(0, 1, At, B1); PG8_BAR; PG8_SCHED;
	v_rcp_f32_e32 v221, v221
	v_mul_f32_e32 v28, v28, v218
	v_mul_f32_e32 v29, v29, v219
	v_mul_f32_e32 v30, v30, v220
	v_mul_f32_e32 v31, v31, v221
	v_mul_f32_e32 v24, v24, v28
	v_mul_f32_e32 v25, v25, v29
	v_mul_f32_e32 v26, v26, v30
	v_mul_f32_e32 v27, v27, v31
	v_mul_f32_e32 v218, 0xbfb8aa3b, v20
	v_mul_f32_e32 v219, 0xbfb8aa3b, v21
	v_mul_f32_e32 v220, 0xbfb8aa3b, v22
	v_mul_f32_e32 v221, 0xbfb8aa3b, v23
	v_exp_f32_e32 v218, v218
	v_exp_f32_e32 v219, v219
	v_exp_f32_e32 v220, v220
	v_exp_f32_e32 v221, v221
	v_add_f32_e32 v218, 1.0, v218
	v_add_f32_e32 v219, 1.0, v219
	v_add_f32_e32 v220, 1.0, v220
	v_add_f32_e32 v221, 1.0, v221
	v_rcp_f32_e32 v218, v218
	v_rcp_f32_e32 v219, v219
	v_rcp_f32_e32 v220, v220
	v_rcp_f32_e32 v221, v221
	v_mul_f32_e32 v20, v20, v218
	v_mul_f32_e32 v21, v21, v219
	v_mul_f32_e32 v22, v22, v220
	v_mul_f32_e32 v23, v23, v221
	v_mul_f32_e32 v16, v16, v20
	v_mul_f32_e32 v17, v17, v21
	v_mul_f32_e32 v18, v18, v22
	v_mul_f32_e32 v19, v19, v23
	v_cvt_pk_bf16_f32 v24, v24, v25
	v_cvt_pk_bf16_f32 v25, v26, v27
	v_cvt_pk_bf16_f32 v26, v16, v17
	v_cvt_pk_bf16_f32 v27, v18, v19
	global_store_dwordx4 v[248:249], v[24:27], off
	v_lshl_add_u64 v[248:249], v[248:249], 0, s[56:57]
	v_mul_f32_e32 v218, 0xbfb8aa3b, v12
	v_mul_f32_e32 v219, 0xbfb8aa3b, v13
	v_mul_f32_e32 v220, 0xbfb8aa3b, v14
	v_mul_f32_e32 v221, 0xbfb8aa3b, v15
	v_exp_f32_e32 v218, v218
	v_exp_f32_e32 v219, v219
	v_exp_f32_e32 v220, v220
	v_exp_f32_e32 v221, v221
	v_add_f32_e32 v218, 1.0, v218
	v_add_f32_e32 v219, 1.0, v219
	v_add_f32_e32 v220, 1.0, v220
	v_add_f32_e32 v221, 1.0, v221
	v_rcp_f32_e32 v218, v218
	v_rcp_f32_e32 v219, v219
	v_rcp_f32_e32 v220, v220
	v_rcp_f32_e32 v221, v221
	v_mul_f32_e32 v12, v12, v218
	v_mul_f32_e32 v13, v13, v219
	v_mul_f32_e32 v14, v14, v220
	v_mul_f32_e32 v15, v15, v221
	v_mul_f32_e32 v8, v8, v12
	v_mul_f32_e32 v9, v9, v13
	v_mul_f32_e32 v10, v10, v14
	v_mul_f32_e32 v11, v11, v15
	v_mul_f32_e32 v218, 0xbfb8aa3b, v4
	v_mul_f32_e32 v219, 0xbfb8aa3b, v5
	v_mul_f32_e32 v220, 0xbfb8aa3b, v6
	v_mul_f32_e32 v221, 0xbfb8aa3b, v7
	v_exp_f32_e32 v218, v218
	v_exp_f32_e32 v219, v219
	v_exp_f32_e32 v220, v220
	v_exp_f32_e32 v221, v221
	v_add_f32_e32 v218, 1.0, v218
	v_add_f32_e32 v219, 1.0, v219
	v_add_f32_e32 v220, 1.0, v220
	v_add_f32_e32 v221, 1.0, v221
	v_rcp_f32_e32 v218, v218
	v_rcp_f32_e32 v219, v219
	v_rcp_f32_e32 v220, v220
	v_rcp_f32_e32 v221, v221
	v_mul_f32_e32 v4, v4, v218
	v_mul_f32_e32 v5, v5, v219
	v_mul_f32_e32 v6, v6, v220
	v_mul_f32_e32 v7, v7, v221
	v_mul_f32_e32 v0, v0, v4
	v_mul_f32_e32 v1, v1, v5
	v_mul_f32_e32 v2, v2, v6
	v_mul_f32_e32 v3, v3, v7
	v_cvt_pk_bf16_f32 v8, v8, v9
	v_cvt_pk_bf16_f32 v9, v10, v11
	v_cvt_pk_bf16_f32 v10, v0, v1
	v_cvt_pk_bf16_f32 v11, v2, v3
	global_store_dwordx4 v[248:249], v[8:11], off
	s_waitcnt vmcnt(16)
	s_waitcnt lgkmcnt(0)
	s_barrier
	s_setprio 1
	s_waitcnt lgkmcnt(0)
	v_mfma_f32_16x16x32_bf16 v[62:65], v[140:143], v[172:175], 0
	v_mfma_f32_16x16x32_bf16 v[58:61], v[148:151], v[172:175], 0
	v_mfma_f32_16x16x32_bf16 v[46:49], v[140:143], v[180:183], 0
	v_mfma_f32_16x16x32_bf16 v[42:45], v[148:151], v[180:183], 0
	v_mfma_f32_16x16x32_bf16 v[28:31], v[140:143], v[188:191], 0
	v_mfma_f32_16x16x32_bf16 v[24:27], v[148:151], v[188:191], 0
	v_mfma_f32_16x16x32_bf16 v[12:15], v[140:143], v[202:205], 0
	v_mfma_f32_16x16x32_bf16 v[8:11], v[148:151], v[202:205], 0
	v_mfma_f32_16x16x32_bf16 v[62:65], v[144:147], v[176:179], v[62:65]
	v_mfma_f32_16x16x32_bf16 v[58:61], v[152:155], v[176:179], v[58:61]
	v_mfma_f32_16x16x32_bf16 v[46:49], v[144:147], v[184:187], v[46:49]
	v_mfma_f32_16x16x32_bf16 v[42:45], v[152:155], v[184:187], v[42:45]
	v_mfma_f32_16x16x32_bf16 v[28:31], v[144:147], v[198:201], v[28:31]
	v_mfma_f32_16x16x32_bf16 v[24:27], v[152:155], v[198:201], v[24:27]
	v_mfma_f32_16x16x32_bf16 v[12:15], v[144:147], v[206:209], v[12:15]
	v_mfma_f32_16x16x32_bf16 v[8:11], v[152:155], v[206:209], v[8:11]
	s_setprio 0
	s_setprio 1
	v_mfma_f32_16x16x32_bf16 v[54:57], v[156:159], v[172:175], 0
	v_mfma_f32_16x16x32_bf16 v[50:53], v[164:167], v[172:175], 0
	v_mfma_f32_16x16x32_bf16 v[38:41], v[156:159], v[180:183], 0
	v_mfma_f32_16x16x32_bf16 v[34:37], v[164:167], v[180:183], 0
	v_mfma_f32_16x16x32_bf16 v[20:23], v[156:159], v[188:191], 0
	v_mfma_f32_16x16x32_bf16 v[16:19], v[164:167], v[188:191], 0
	v_mfma_f32_16x16x32_bf16 v[4:7], v[156:159], v[202:205], 0
	v_mfma_f32_16x16x32_bf16 v[0:3], v[164:167], v[202:205], 0
	v_mfma_f32_16x16x32_bf16 v[54:57], v[160:163], v[176:179], v[54:57]
	v_mfma_f32_16x16x32_bf16 v[50:53], v[168:171], v[176:179], v[50:53]
	v_mfma_f32_16x16x32_bf16 v[38:41], v[160:163], v[184:187], v[38:41]
	v_mfma_f32_16x16x32_bf16 v[34:37], v[168:171], v[184:187], v[34:37]
	v_mfma_f32_16x16x32_bf16 v[20:23], v[160:163], v[198:201], v[20:23]
	v_mfma_f32_16x16x32_bf16 v[16:19], v[168:171], v[198:201], v[16:19]
	v_mfma_f32_16x16x32_bf16 v[4:7], v[160:163], v[206:209], v[4:7]
	v_mfma_f32_16x16x32_bf16 v[0:3], v[168:171], v[206:209], v[0:3]
	s_setprio 0
	s_barrier
	s_add_i32 s47, 0, 0x18000
	s_add_i32 s50, 0, 0x1c000
	v_add_u32_e32 v152, s47, v137
	v_add_u32_e32 v168, s50, v137
	ds_read_b128 v[140:143], v152
	ds_read_b128 v[144:147], v152 offset:1024
	ds_read_b128 v[148:151], v152 offset:2048
	ds_read_b128 v[152:155], v152 offset:3072
	ds_read_b128 v[156:159], v168
	ds_read_b128 v[160:163], v168 offset:1024
	ds_read_b128 v[164:167], v168 offset:2048
	ds_read_b128 v[168:171], v168 offset:3072
	s_add_u32 s48, s48, 0x80000
	s_addc_u32 s49, s49, 0
	s_mov_b32 m0, s38
	v_lshl_add_u64 v[216:217], s[48:49], 0, v[32:33]
	ds_read_b128 v[172:175], v139 offset:32768
	ds_read_b128 v[176:179], v139 offset:33792
	ds_read_b128 v[180:183], v139 offset:34816
	ds_read_b128 v[184:187], v139 offset:35840
	ds_read_b128 v[188:191], v139 offset:36864
	ds_read_b128 v[198:201], v139 offset:37888
	ds_read_b128 v[202:205], v139 offset:38912
	ds_read_b128 v[206:209], v139 offset:39936
	global_load_lds_dwordx4 v[216:217], off
	v_lshl_add_u64 v[216:217], s[48:49], 0, v[130:131]
	s_mov_b32 m0, s39
	s_nop 0
	global_load_lds_dwordx4 v[216:217], off
	s_waitcnt vmcnt(13)
	s_waitcnt lgkmcnt(0)
	s_barrier
; #define PG8_STAGE(bufoff, gbase, voff) do { _Pragma("unroll") for (int _i = 0; _i < 2; ++_i) \
;         __builtin_amdgcn_global_load_lds((const unsigned*)((const char*)(gbase) + (voff)[_i]), (PG8_LAS unsigned*)(lds + (bufoff) + ldsw + _i * 8192), 16, 0, 0); } while (0)
; #define PG8_LDA(dst, b, h) do { _Pragma("unroll") for (int m = 0; m < 4; ++m) _Pragma("unroll") for (int k = 0; k < 2; ++k) dst[m][k] = *(const PG8_LAS bf16x8*)(lds + PG8_SA(b, h) + aoff + m * 2048 + k * 1024); } while (0)
; #define PG8_MMA(ai, bj, At, Bt) do { __builtin_amdgcn_s_setprio(1); _Pragma("unroll") for (int m = 0; m < 4; ++m) _Pragma("unroll") for (int n = 0; n < 2; ++n) _Pragma("unroll") for (int k = 0; k < 2; ++k) \
;         acc[ai][bj][m][n] = __builtin_amdgcn_mfma_f32_16x16x32_bf16(Bt[n][k], At[m][k], acc[ai][bj][m][n], 0, 0, 0); __builtin_amdgcn_s_setprio(0); } while (0)
; #define PG8_WAIT_V(n) asm volatile("s_waitcnt vmcnt(" #n ")" ::: "memory")
; #define PG8_WAIT_L(n) asm volatile("s_waitcnt lgkmcnt(" #n ")" ::: "memory")
; #define PG8_BAR __builtin_amdgcn_s_barrier()
; #define PG8_SCHED __builtin_amdgcn_sched_barrier(0)
; template <class Epi, class Sched, bool ALIGN_EPI = false, bool SP2 = false, bool KHOOK = false>
; __device__ __forceinline__ void gemm_phase(PG8_LAS unsigned char* lds, const Gemm g, const Sched& S, const Epi& E, const int tid_in) {
;     ...
;             PG8_WAIT_V(8); PG8_WAIT_L(0); PG8_BAR; PG8_MMA(0, 0, At, B0); PG8_MMA(0, 1, At, B1); PG8_BAR; PG8_SCHED;
;             PG8_LDA(At, 1, 1); PG8_STAGE(PG8_SB(1, 0), b3, voffB); PG8_STAGE(PG8_SB(1, 1), b3 + hstep, voffB); PG8_STAGE(PG8_SA(1, 0), a3, voffA);
;             PG8_WAIT_V(8); PG8_WAIT_L(0); PG8_BAR; PG8_MMA(1, 0, At, B0); PG8_MMA(1, 1, At, B1); PG8_BAR; PG8_SCHED;
	s_setprio 1
	s_waitcnt lgkmcnt(0)
	v_mfma_f32_16x16x32_bf16 v[126:129], v[140:143], v[172:175], v[126:129]
	v_mfma_f32_16x16x32_bf16 v[122:125], v[148:151], v[172:175], v[122:125]
	v_mfma_f32_16x16x32_bf16 v[110:113], v[140:143], v[180:183], v[110:113]
	v_mfma_f32_16x16x32_bf16 v[106:109], v[148:151], v[180:183], v[106:109]
	v_mfma_f32_16x16x32_bf16 v[94:97], v[140:143], v[188:191], v[94:97]
	v_mfma_f32_16x16x32_bf16 v[90:93], v[148:151], v[188:191], v[90:93]
	v_mfma_f32_16x16x32_bf16 v[78:81], v[140:143], v[202:205], v[78:81]
	v_mfma_f32_16x16x32_bf16 v[74:77], v[148:151], v[202:205], v[74:77]
	v_mfma_f32_16x16x32_bf16 v[126:129], v[144:147], v[176:179], v[126:129]
	v_mfma_f32_16x16x32_bf16 v[122:125], v[152:155], v[176:179], v[122:125]
	v_mfma_f32_16x16x32_bf16 v[110:113], v[144:147], v[184:187], v[110:113]
	v_mfma_f32_16x16x32_bf16 v[106:109], v[152:155], v[184:187], v[106:109]
	v_mfma_f32_16x16x32_bf16 v[94:97], v[144:147], v[198:201], v[94:97]
	v_mfma_f32_16x16x32_bf16 v[90:93], v[152:155], v[198:201], v[90:93]
	v_mfma_f32_16x16x32_bf16 v[78:81], v[144:147], v[206:209], v[78:81]
	v_mfma_f32_16x16x32_bf16 v[74:77], v[152:155], v[206:209], v[74:77]
	s_setprio 0
	s_setprio 1
	v_mfma_f32_16x16x32_bf16 v[118:121], v[156:159], v[172:175], v[118:121]
	v_mfma_f32_16x16x32_bf16 v[114:117], v[164:167], v[172:175], v[114:117]
	v_mfma_f32_16x16x32_bf16 v[102:105], v[156:159], v[180:183], v[102:105]
	v_mfma_f32_16x16x32_bf16 v[98:101], v[164:167], v[180:183], v[98:101]
	v_mfma_f32_16x16x32_bf16 v[86:89], v[156:159], v[188:191], v[86:89]
	v_mfma_f32_16x16x32_bf16 v[82:85], v[164:167], v[188:191], v[82:85]
	v_mfma_f32_16x16x32_bf16 v[70:73], v[156:159], v[202:205], v[70:73]
	v_mfma_f32_16x16x32_bf16 v[66:69], v[164:167], v[202:205], v[66:69]
	v_mfma_f32_16x16x32_bf16 v[118:121], v[160:163], v[176:179], v[118:121]
	v_mfma_f32_16x16x32_bf16 v[114:117], v[168:171], v[176:179], v[114:117]
	v_mfma_f32_16x16x32_bf16 v[102:105], v[160:163], v[184:187], v[102:105]
	v_mfma_f32_16x16x32_bf16 v[98:101], v[168:171], v[184:187], v[98:101]
	v_mfma_f32_16x16x32_bf16 v[86:89], v[160:163], v[198:201], v[86:89]
	v_mfma_f32_16x16x32_bf16 v[82:85], v[168:171], v[198:201], v[82:85]
	v_mfma_f32_16x16x32_bf16 v[70:73], v[160:163], v[206:209], v[70:73]
	v_mfma_f32_16x16x32_bf16 v[66:69], v[168:171], v[206:209], v[66:69]
	s_setprio 0
	s_barrier
	s_add_i32 s47, s47, s33
	v_lshl_add_u64 v[192:193], v[192:193], 0, s[90:91]
	s_mov_b32 m0, s47
	ds_read_b128 v[172:175], v139 offset:49152
	ds_read_b128 v[176:179], v139 offset:50176
	ds_read_b128 v[180:183], v139 offset:51200
	ds_read_b128 v[184:187], v139 offset:52224
	ds_read_b128 v[188:191], v139 offset:53248
	ds_read_b128 v[198:201], v139 offset:54272
	ds_read_b128 v[202:205], v139 offset:55296
	ds_read_b128 v[206:209], v139 offset:56320
	global_load_lds_dwordx4 v[192:193], off
	s_add_i32 m0, s47, 0x2000
	s_add_u32 s30, s30, 0x80080
	v_lshl_add_u64 v[192:193], v[210:211], 0, s[90:91]
	s_addc_u32 s31, s31, 0
	s_add_i32 s47, s50, s33
	global_load_lds_dwordx4 v[192:193], off
	v_lshl_add_u64 v[192:193], s[30:31], 0, v[32:33]
	s_mov_b32 m0, s47
	s_nop 0
	global_load_lds_dwordx4 v[192:193], off
	v_lshl_add_u64 v[192:193], s[30:31], 0, v[130:131]
	s_add_i32 m0, s47, 0x2000
	s_nop 0
	global_load_lds_dwordx4 v[192:193], off
	v_lshl_add_u64 v[192:193], v[212:213], 0, s[90:91]
	s_mov_b32 m0, s40
	s_nop 0
	global_load_lds_dwordx4 v[192:193], off
	v_lshl_add_u64 v[192:193], v[214:215], 0, s[90:91]
	s_mov_b32 m0, s41
	s_nop 0
	global_load_lds_dwordx4 v[192:193], off
	s_waitcnt vmcnt(11)
	s_waitcnt lgkmcnt(0)
	s_barrier
	s_setprio 1
	s_waitcnt lgkmcnt(0)
	v_mfma_f32_16x16x32_bf16 v[62:65], v[140:143], v[172:175], v[62:65]
	v_mfma_f32_16x16x32_bf16 v[58:61], v[148:151], v[172:175], v[58:61]
	v_mfma_f32_16x16x32_bf16 v[46:49], v[140:143], v[180:183], v[46:49]
	v_mfma_f32_16x16x32_bf16 v[42:45], v[148:151], v[180:183], v[42:45]
	v_mfma_f32_16x16x32_bf16 v[28:31], v[140:143], v[188:191], v[28:31]
	v_mfma_f32_16x16x32_bf16 v[24:27], v[148:151], v[188:191], v[24:27]
	v_mfma_f32_16x16x32_bf16 v[12:15], v[140:143], v[202:205], v[12:15]
	v_mfma_f32_16x16x32_bf16 v[8:11], v[148:151], v[202:205], v[8:11]
	v_mfma_f32_16x16x32_bf16 v[62:65], v[144:147], v[176:179], v[62:65]
	v_mfma_f32_16x16x32_bf16 v[58:61], v[152:155], v[176:179], v[58:61]
	v_mfma_f32_16x16x32_bf16 v[46:49], v[144:147], v[184:187], v[46:49]
	v_mfma_f32_16x16x32_bf16 v[42:45], v[152:155], v[184:187], v[42:45]
	v_mfma_f32_16x16x32_bf16 v[28:31], v[144:147], v[198:201], v[28:31]
	v_mfma_f32_16x16x32_bf16 v[24:27], v[152:155], v[198:201], v[24:27]
	v_mfma_f32_16x16x32_bf16 v[12:15], v[144:147], v[206:209], v[12:15]
	v_mfma_f32_16x16x32_bf16 v[8:11], v[152:155], v[206:209], v[8:11]
	s_setprio 0
	s_setprio 1
	v_mfma_f32_16x16x32_bf16 v[54:57], v[156:159], v[172:175], v[54:57]
	v_mfma_f32_16x16x32_bf16 v[50:53], v[164:167], v[172:175], v[50:53]
	v_mfma_f32_16x16x32_bf16 v[38:41], v[156:159], v[180:183], v[38:41]
	v_mfma_f32_16x16x32_bf16 v[34:37], v[164:167], v[180:183], v[34:37]
	v_mfma_f32_16x16x32_bf16 v[20:23], v[156:159], v[188:191], v[20:23]
	v_mfma_f32_16x16x32_bf16 v[16:19], v[164:167], v[188:191], v[16:19]
	v_mfma_f32_16x16x32_bf16 v[4:7], v[156:159], v[202:205], v[4:7]
	v_mfma_f32_16x16x32_bf16 v[0:3], v[164:167], v[202:205], v[0:3]
	v_mfma_f32_16x16x32_bf16 v[54:57], v[160:163], v[176:179], v[54:57]
	v_mfma_f32_16x16x32_bf16 v[50:53], v[168:171], v[176:179], v[50:53]
	v_mfma_f32_16x16x32_bf16 v[38:41], v[160:163], v[184:187], v[38:41]
	v_mfma_f32_16x16x32_bf16 v[34:37], v[168:171], v[184:187], v[34:37]
	v_mfma_f32_16x16x32_bf16 v[20:23], v[160:163], v[198:201], v[20:23]
	v_mfma_f32_16x16x32_bf16 v[16:19], v[168:171], v[198:201], v[16:19]
	v_mfma_f32_16x16x32_bf16 v[4:7], v[160:163], v[206:209], v[4:7]
	v_mfma_f32_16x16x32_bf16 v[0:3], v[168:171], v[206:209], v[0:3]
	s_setprio 0
	s_barrier
	s_add_i32 s46, s46, 2
	s_add_u32 s26, s26, 0x100
	s_addc_u32 s27, s27, 0
	s_add_u32 s44, s44, 0x100
	s_addc_u32 s45, s45, 0
	s_cmp_gt_u32 s46, 29
; #define PG8_STAGE(bufoff, gbase, voff) do { _Pragma("unroll") for (int _i = 0; _i < 2; ++_i) \
;         __builtin_amdgcn_global_load_lds((const unsigned*)((const char*)(gbase) + (voff)[_i]), (PG8_LAS unsigned*)(lds + (bufoff) + ldsw + _i * 8192), 16, 0, 0); } while (0)
; #define PG8_LDA(dst, b, h) do { _Pragma("unroll") for (int m = 0; m < 4; ++m) _Pragma("unroll") for (int k = 0; k < 2; ++k) dst[m][k] = *(const PG8_LAS bf16x8*)(lds + PG8_SA(b, h) + aoff + m * 2048 + k * 1024); } while (0)
; #define PG8_LDB(dst, b, h) do { _Pragma("unroll") for (int n = 0; n < 2; ++n) _Pragma("unroll") for (int k = 0; k < 2; ++k) dst[n][k] = *(const PG8_LAS bf16x8*)(lds + PG8_SB(b, h) + boff + n * 2048 + k * 1024); } while (0)
; #define PG8_MMA(ai, bj, At, Bt) do { __builtin_amdgcn_s_setprio(1); _Pragma("unroll") for (int m = 0; m < 4; ++m) _Pragma("unroll") for (int n = 0; n < 2; ++n) _Pragma("unroll") for (int k = 0; k < 2; ++k) \
;         acc[ai][bj][m][n] = __builtin_amdgcn_mfma_f32_16x16x32_bf16(Bt[n][k], At[m][k], acc[ai][bj][m][n], 0, 0, 0); __builtin_amdgcn_s_setprio(0); } while (0)
; #define PG8_WAIT_V(n) asm volatile("s_waitcnt vmcnt(" #n ")" ::: "memory")
; #define PG8_WAIT_L(n) asm volatile("s_waitcnt lgkmcnt(" #n ")" ::: "memory")
; #define PG8_BAR __builtin_amdgcn_s_barrier()
; #define PG8_SCHED __builtin_amdgcn_sched_barrier(0)
; template <class Epi, class Sched, bool ALIGN_EPI = false, bool SP2 = false, bool KHOOK = false>
; __device__ __forceinline__ void gemm_phase(PG8_LAS unsigned char* lds, const Gemm g, const Sched& S, const Epi& E, const int tid_in) {
;     ...
;             const char* a2 = last ? nA : cA + (size_t)(t + 2) * kstep; const char* b2 = last ? nB : cB + (size_t)(t + 2) * kstep;
;             const char* a3 = a2 + kstep; const char* b3 = b2 + kstep;
;             if (last && has_next) S.a_ready(nxt);
;             if constexpr (SP2) {
;             PG8_LDB(B0, 0, 0); PG8_LDB(B1, 0, 1); PG8_SCHED; PG8_LDA(At, 0, 0); PG8_STAGE(PG8_SA(1, 1), a1 + hstep, voffA);
;             PG8_WAIT_V(8); PG8_WAIT_L(0); PG8_BAR; PG8_MMA(0, 0, At, B0); PG8_MMA(0, 1, At, B1); PG8_BAR; PG8_SCHED;
;             PG8_LDA(At, 0, 1); PG8_STAGE(PG8_SB(0, 0), b2, voffB); PG8_STAGE(PG8_SB(0, 1), b2 + hstep, voffB); PG8_STAGE(PG8_SA(0, 0), a2, voffA);
;             PG8_WAIT_V(8); PG8_WAIT_L(0); PG8_BAR; PG8_MMA(1, 0, At, B0); PG8_MMA(1, 1, At, B1); PG8_BAR; PG8_SCHED;
.LBB0_1063:
	s_add_u32 s30, s26, 0xfff80080
	s_addc_u32 s31, s27, -1
	s_add_i32 s47, 0, 0x10000
	s_cmp_eq_u32 s46, 28
	s_cselect_b32 s49, s13, s31
	s_cselect_b32 s48, s24, s30
	s_cselect_b32 s31, s11, s45
	s_cselect_b32 s30, s25, s44
	s_add_i32 s52, 0, 0x14000
	v_add_u32_e32 v152, s47, v137
	v_add_u32_e32 v168, s52, v137
	ds_read_b128 v[140:143], v152
	ds_read_b128 v[144:147], v152 offset:1024
	ds_read_b128 v[148:151], v152 offset:2048
	ds_read_b128 v[152:155], v152 offset:3072
	ds_read_b128 v[156:159], v168
	ds_read_b128 v[160:163], v168 offset:1024
	ds_read_b128 v[164:167], v168 offset:2048
	ds_read_b128 v[168:171], v168 offset:3072
	v_lshl_add_u64 v[192:193], s[26:27], 0, v[132:133]
	s_add_i32 m0, s36, 0xc000
	ds_read_b128 v[172:175], v139
	ds_read_b128 v[176:179], v139 offset:1024
	ds_read_b128 v[180:183], v139 offset:2048
	ds_read_b128 v[184:187], v139 offset:3072
	ds_read_b128 v[188:191], v139 offset:4096
	ds_read_b128 v[198:201], v139 offset:5120
	ds_read_b128 v[202:205], v139 offset:6144
	ds_read_b128 v[206:209], v139 offset:7168
	global_load_lds_dwordx4 v[192:193], off
	v_lshl_add_u64 v[192:193], s[26:27], 0, v[134:135]
	s_add_i32 m0, s36, 0xe000
	s_nop 0
	global_load_lds_dwordx4 v[192:193], off
	s_waitcnt vmcnt(8)
	s_waitcnt lgkmcnt(0)
	s_barrier
	s_setprio 1
	s_waitcnt lgkmcnt(0)
	v_mfma_f32_16x16x32_bf16 v[126:129], v[140:143], v[172:175], v[126:129]
	v_mfma_f32_16x16x32_bf16 v[122:125], v[148:151], v[172:175], v[122:125]
	v_mfma_f32_16x16x32_bf16 v[110:113], v[140:143], v[180:183], v[110:113]
	v_mfma_f32_16x16x32_bf16 v[106:109], v[148:151], v[180:183], v[106:109]
	v_mfma_f32_16x16x32_bf16 v[94:97], v[140:143], v[188:191], v[94:97]
	v_mfma_f32_16x16x32_bf16 v[90:93], v[148:151], v[188:191], v[90:93]
	v_mfma_f32_16x16x32_bf16 v[78:81], v[140:143], v[202:205], v[78:81]
	v_mfma_f32_16x16x32_bf16 v[74:77], v[148:151], v[202:205], v[74:77]
	v_mfma_f32_16x16x32_bf16 v[126:129], v[144:147], v[176:179], v[126:129]
	v_mfma_f32_16x16x32_bf16 v[122:125], v[152:155], v[176:179], v[122:125]
	v_mfma_f32_16x16x32_bf16 v[110:113], v[144:147], v[184:187], v[110:113]
	v_mfma_f32_16x16x32_bf16 v[106:109], v[152:155], v[184:187], v[106:109]
	v_mfma_f32_16x16x32_bf16 v[94:97], v[144:147], v[198:201], v[94:97]
	v_mfma_f32_16x16x32_bf16 v[90:93], v[152:155], v[198:201], v[90:93]
	v_mfma_f32_16x16x32_bf16 v[78:81], v[144:147], v[206:209], v[78:81]
	v_mfma_f32_16x16x32_bf16 v[74:77], v[152:155], v[206:209], v[74:77]
	s_setprio 0
	s_setprio 1
	v_mfma_f32_16x16x32_bf16 v[118:121], v[156:159], v[172:175], v[118:121]
	v_mfma_f32_16x16x32_bf16 v[114:117], v[164:167], v[172:175], v[114:117]
	v_mfma_f32_16x16x32_bf16 v[102:105], v[156:159], v[180:183], v[102:105]
	v_mfma_f32_16x16x32_bf16 v[98:101], v[164:167], v[180:183], v[98:101]
	v_mfma_f32_16x16x32_bf16 v[86:89], v[156:159], v[188:191], v[86:89]
	v_mfma_f32_16x16x32_bf16 v[82:85], v[164:167], v[188:191], v[82:85]
	v_mfma_f32_16x16x32_bf16 v[70:73], v[156:159], v[202:205], v[70:73]
	v_mfma_f32_16x16x32_bf16 v[66:69], v[164:167], v[202:205], v[66:69]
	v_mfma_f32_16x16x32_bf16 v[118:121], v[160:163], v[176:179], v[118:121]
	v_mfma_f32_16x16x32_bf16 v[114:117], v[168:171], v[176:179], v[114:117]
	v_mfma_f32_16x16x32_bf16 v[102:105], v[160:163], v[184:187], v[102:105]
	v_mfma_f32_16x16x32_bf16 v[98:101], v[168:171], v[184:187], v[98:101]
	v_mfma_f32_16x16x32_bf16 v[86:89], v[160:163], v[198:201], v[86:89]
	v_mfma_f32_16x16x32_bf16 v[82:85], v[168:171], v[198:201], v[82:85]
	v_mfma_f32_16x16x32_bf16 v[70:73], v[160:163], v[206:209], v[70:73]
	v_mfma_f32_16x16x32_bf16 v[66:69], v[168:171], v[206:209], v[66:69]
	s_setprio 0
	s_barrier
	s_add_i32 s47, s47, s33
	v_lshl_add_u64 v[192:193], s[30:31], 0, v[32:33]
	s_mov_b32 m0, s47
	ds_read_b128 v[172:175], v139 offset:16384
	ds_read_b128 v[176:179], v139 offset:17408
	ds_read_b128 v[180:183], v139 offset:18432
	ds_read_b128 v[184:187], v139 offset:19456
	ds_read_b128 v[188:191], v139 offset:20480
	ds_read_b128 v[198:201], v139 offset:21504
	ds_read_b128 v[202:205], v139 offset:22528
	ds_read_b128 v[206:209], v139 offset:23552
	global_load_lds_dwordx4 v[192:193], off
	s_add_i32 m0, s47, 0x2000
	s_add_u32 s50, s30, 0x80000
	v_lshl_add_u64 v[210:211], s[30:31], 0, v[130:131]
	s_addc_u32 s51, s31, 0
	s_add_i32 s47, s52, s33
	global_load_lds_dwordx4 v[210:211], off
	v_lshl_add_u64 v[212:213], s[50:51], 0, v[32:33]
	s_mov_b32 m0, s47
	v_lshl_add_u64 v[214:215], s[48:49], 0, v[130:131]
	global_load_lds_dwordx4 v[212:213], off
	v_lshl_add_u64 v[212:213], s[50:51], 0, v[130:131]
	s_add_i32 m0, s47, 0x2000
	s_nop 0
	global_load_lds_dwordx4 v[212:213], off
	v_lshl_add_u64 v[212:213], s[48:49], 0, v[32:33]
	s_mov_b32 m0, s36
	s_nop 0
	global_load_lds_dwordx4 v[212:213], off
	s_mov_b32 m0, s37
	s_nop 0
	global_load_lds_dwordx4 v[214:215], off
	s_waitcnt vmcnt(8)
	s_waitcnt lgkmcnt(0)
	s_barrier
; #define PG8_STAGE(bufoff, gbase, voff) do { _Pragma("unroll") for (int _i = 0; _i < 2; ++_i) \
;         __builtin_amdgcn_global_load_lds((const unsigned*)((const char*)(gbase) + (voff)[_i]), (PG8_LAS unsigned*)(lds + (bufoff) + ldsw + _i * 8192), 16, 0, 0); } while (0)
; #define PG8_LDA(dst, b, h) do { _Pragma("unroll") for (int m = 0; m < 4; ++m) _Pragma("unroll") for (int k = 0; k < 2; ++k) dst[m][k] = *(const PG8_LAS bf16x8*)(lds + PG8_SA(b, h) + aoff + m * 2048 + k * 1024); } while (0)
; #define PG8_LDB(dst, b, h) do { _Pragma("unroll") for (int n = 0; n < 2; ++n) _Pragma("unroll") for (int k = 0; k < 2; ++k) dst[n][k] = *(const PG8_LAS bf16x8*)(lds + PG8_SB(b, h) + boff + n * 2048 + k * 1024); } while (0)
; #define PG8_MMA(ai, bj, At, Bt) do { __builtin_amdgcn_s_setprio(1); _Pragma("unroll") for (int m = 0; m < 4; ++m) _Pragma("unroll") for (int n = 0; n < 2; ++n) _Pragma("unroll") for (int k = 0; k < 2; ++k) \
;         acc[ai][bj][m][n] = __builtin_amdgcn_mfma_f32_16x16x32_bf16(Bt[n][k], At[m][k], acc[ai][bj][m][n], 0, 0, 0); __builtin_amdgcn_s_setprio(0); } while (0)
; #define PG8_WAIT_V(n) asm volatile("s_waitcnt vmcnt(" #n ")" ::: "memory")
; #define PG8_WAIT_L(n) asm volatile("s_waitcnt lgkmcnt(" #n ")" ::: "memory")
; #define PG8_BAR __builtin_amdgcn_s_barrier()
; #define PG8_SCHED __builtin_amdgcn_sched_barrier(0)
; template <class Epi, class Sched, bool ALIGN_EPI = false, bool SP2 = false, bool KHOOK = false>
; __device__ __forceinline__ void gemm_phase(PG8_LAS unsigned char* lds, const Gemm g, const Sched& S, const Epi& E, const int tid_in) {
;     ...
;             PG8_WAIT_V(8); PG8_WAIT_L(0); PG8_BAR; PG8_MMA(1, 0, At, B0); PG8_MMA(1, 1, At, B1); PG8_BAR; PG8_SCHED;
;             PG8_LDB(B0, 1, 0); PG8_LDB(B1, 1, 1); PG8_SCHED; PG8_LDA(At, 1, 0); PG8_STAGE(PG8_SA(0, 1), a2 + hstep, voffA);
;             PG8_WAIT_V(8); PG8_WAIT_L(0); PG8_BAR; PG8_MMA(0, 0, At, B0); PG8_MMA(0, 1, At, B1); PG8_BAR; PG8_SCHED;
	s_setprio 1
	s_waitcnt lgkmcnt(0)
	v_mfma_f32_16x16x32_bf16 v[62:65], v[140:143], v[172:175], v[62:65]
	v_mfma_f32_16x16x32_bf16 v[58:61], v[148:151], v[172:175], v[58:61]
	v_mfma_f32_16x16x32_bf16 v[46:49], v[140:143], v[180:183], v[46:49]
	v_mfma_f32_16x16x32_bf16 v[42:45], v[148:151], v[180:183], v[42:45]
	v_mfma_f32_16x16x32_bf16 v[28:31], v[140:143], v[188:191], v[28:31]
	v_mfma_f32_16x16x32_bf16 v[24:27], v[148:151], v[188:191], v[24:27]
	v_mfma_f32_16x16x32_bf16 v[12:15], v[140:143], v[202:205], v[12:15]
	v_mfma_f32_16x16x32_bf16 v[8:11], v[148:151], v[202:205], v[8:11]
	v_mfma_f32_16x16x32_bf16 v[62:65], v[144:147], v[176:179], v[62:65]
	v_mfma_f32_16x16x32_bf16 v[58:61], v[152:155], v[176:179], v[58:61]
	v_mfma_f32_16x16x32_bf16 v[46:49], v[144:147], v[184:187], v[46:49]
	v_mfma_f32_16x16x32_bf16 v[42:45], v[152:155], v[184:187], v[42:45]
	v_mfma_f32_16x16x32_bf16 v[28:31], v[144:147], v[198:201], v[28:31]
	v_mfma_f32_16x16x32_bf16 v[24:27], v[152:155], v[198:201], v[24:27]
	v_mfma_f32_16x16x32_bf16 v[12:15], v[144:147], v[206:209], v[12:15]
	v_mfma_f32_16x16x32_bf16 v[8:11], v[152:155], v[206:209], v[8:11]
	s_setprio 0
	s_setprio 1
	v_mfma_f32_16x16x32_bf16 v[54:57], v[156:159], v[172:175], v[54:57]
	v_mfma_f32_16x16x32_bf16 v[50:53], v[164:167], v[172:175], v[50:53]
	v_mfma_f32_16x16x32_bf16 v[38:41], v[156:159], v[180:183], v[38:41]
	v_mfma_f32_16x16x32_bf16 v[34:37], v[164:167], v[180:183], v[34:37]
	v_mfma_f32_16x16x32_bf16 v[20:23], v[156:159], v[188:191], v[20:23]
	v_mfma_f32_16x16x32_bf16 v[16:19], v[164:167], v[188:191], v[16:19]
	v_mfma_f32_16x16x32_bf16 v[4:7], v[156:159], v[202:205], v[4:7]
	v_mfma_f32_16x16x32_bf16 v[0:3], v[164:167], v[202:205], v[0:3]
	v_mfma_f32_16x16x32_bf16 v[54:57], v[160:163], v[176:179], v[54:57]
	v_mfma_f32_16x16x32_bf16 v[50:53], v[168:171], v[176:179], v[50:53]
	v_mfma_f32_16x16x32_bf16 v[38:41], v[160:163], v[184:187], v[38:41]
	v_mfma_f32_16x16x32_bf16 v[34:37], v[168:171], v[184:187], v[34:37]
	v_mfma_f32_16x16x32_bf16 v[20:23], v[160:163], v[198:201], v[20:23]
	v_mfma_f32_16x16x32_bf16 v[16:19], v[168:171], v[198:201], v[16:19]
	v_mfma_f32_16x16x32_bf16 v[4:7], v[160:163], v[206:209], v[4:7]
	v_mfma_f32_16x16x32_bf16 v[0:3], v[168:171], v[206:209], v[0:3]
	s_setprio 0
	s_barrier
	s_add_i32 s47, 0, 0x18000
	s_add_i32 s50, 0, 0x1c000
	v_add_u32_e32 v152, s47, v137
	v_add_u32_e32 v168, s50, v137
	ds_read_b128 v[140:143], v152
	ds_read_b128 v[144:147], v152 offset:1024
	ds_read_b128 v[148:151], v152 offset:2048
	ds_read_b128 v[152:155], v152 offset:3072
	ds_read_b128 v[156:159], v168
	ds_read_b128 v[160:163], v168 offset:1024
	ds_read_b128 v[164:167], v168 offset:2048
	ds_read_b128 v[168:171], v168 offset:3072
	s_add_u32 s48, s48, 0x80000
	s_addc_u32 s49, s49, 0
	s_mov_b32 m0, s38
	v_lshl_add_u64 v[216:217], s[48:49], 0, v[32:33]
	ds_read_b128 v[172:175], v139 offset:32768
	ds_read_b128 v[176:179], v139 offset:33792
	ds_read_b128 v[180:183], v139 offset:34816
	ds_read_b128 v[184:187], v139 offset:35840
	ds_read_b128 v[188:191], v139 offset:36864
	ds_read_b128 v[198:201], v139 offset:37888
	ds_read_b128 v[202:205], v139 offset:38912
	ds_read_b128 v[206:209], v139 offset:39936
	global_load_lds_dwordx4 v[216:217], off
	v_lshl_add_u64 v[216:217], s[48:49], 0, v[130:131]
	s_mov_b32 m0, s39
	s_nop 0
	global_load_lds_dwordx4 v[216:217], off
	s_waitcnt vmcnt(8)
	s_waitcnt lgkmcnt(0)
	s_barrier
	s_setprio 1
	s_waitcnt lgkmcnt(0)
	v_mfma_f32_16x16x32_bf16 v[126:129], v[140:143], v[172:175], v[126:129]
	v_mfma_f32_16x16x32_bf16 v[122:125], v[148:151], v[172:175], v[122:125]
	v_mfma_f32_16x16x32_bf16 v[110:113], v[140:143], v[180:183], v[110:113]
	v_mfma_f32_16x16x32_bf16 v[106:109], v[148:151], v[180:183], v[106:109]
	v_mfma_f32_16x16x32_bf16 v[94:97], v[140:143], v[188:191], v[94:97]
	v_mfma_f32_16x16x32_bf16 v[90:93], v[148:151], v[188:191], v[90:93]
	v_mfma_f32_16x16x32_bf16 v[78:81], v[140:143], v[202:205], v[78:81]
	v_mfma_f32_16x16x32_bf16 v[74:77], v[148:151], v[202:205], v[74:77]
	v_mfma_f32_16x16x32_bf16 v[126:129], v[144:147], v[176:179], v[126:129]
	v_mfma_f32_16x16x32_bf16 v[122:125], v[152:155], v[176:179], v[122:125]
	v_mfma_f32_16x16x32_bf16 v[110:113], v[144:147], v[184:187], v[110:113]
	v_mfma_f32_16x16x32_bf16 v[106:109], v[152:155], v[184:187], v[106:109]
	v_mfma_f32_16x16x32_bf16 v[94:97], v[144:147], v[198:201], v[94:97]
	v_mfma_f32_16x16x32_bf16 v[90:93], v[152:155], v[198:201], v[90:93]
	v_mfma_f32_16x16x32_bf16 v[78:81], v[144:147], v[206:209], v[78:81]
	v_mfma_f32_16x16x32_bf16 v[74:77], v[152:155], v[206:209], v[74:77]
	s_setprio 0
	s_setprio 1
	v_mfma_f32_16x16x32_bf16 v[118:121], v[156:159], v[172:175], v[118:121]
	v_mfma_f32_16x16x32_bf16 v[114:117], v[164:167], v[172:175], v[114:117]
	v_mfma_f32_16x16x32_bf16 v[102:105], v[156:159], v[180:183], v[102:105]
	v_mfma_f32_16x16x32_bf16 v[98:101], v[164:167], v[180:183], v[98:101]
	v_mfma_f32_16x16x32_bf16 v[86:89], v[156:159], v[188:191], v[86:89]
	v_mfma_f32_16x16x32_bf16 v[82:85], v[164:167], v[188:191], v[82:85]
	v_mfma_f32_16x16x32_bf16 v[70:73], v[156:159], v[202:205], v[70:73]
	v_mfma_f32_16x16x32_bf16 v[66:69], v[164:167], v[202:205], v[66:69]
	v_mfma_f32_16x16x32_bf16 v[118:121], v[160:163], v[176:179], v[118:121]
	v_mfma_f32_16x16x32_bf16 v[114:117], v[168:171], v[176:179], v[114:117]
	v_mfma_f32_16x16x32_bf16 v[102:105], v[160:163], v[184:187], v[102:105]
	v_mfma_f32_16x16x32_bf16 v[98:101], v[168:171], v[184:187], v[98:101]
	v_mfma_f32_16x16x32_bf16 v[86:89], v[160:163], v[198:201], v[86:89]
	v_mfma_f32_16x16x32_bf16 v[82:85], v[168:171], v[198:201], v[82:85]
	v_mfma_f32_16x16x32_bf16 v[70:73], v[160:163], v[206:209], v[70:73]
	v_mfma_f32_16x16x32_bf16 v[66:69], v[168:171], v[206:209], v[66:69]
	s_setprio 0
	s_barrier
; #define PG8_STAGE(bufoff, gbase, voff) do { _Pragma("unroll") for (int _i = 0; _i < 2; ++_i) \
;         __builtin_amdgcn_global_load_lds((const unsigned*)((const char*)(gbase) + (voff)[_i]), (PG8_LAS unsigned*)(lds + (bufoff) + ldsw + _i * 8192), 16, 0, 0); } while (0)
; #define PG8_LDA(dst, b, h) do { _Pragma("unroll") for (int m = 0; m < 4; ++m) _Pragma("unroll") for (int k = 0; k < 2; ++k) dst[m][k] = *(const PG8_LAS bf16x8*)(lds + PG8_SA(b, h) + aoff + m * 2048 + k * 1024); } while (0)
; #define PG8_WAIT_V(n) asm volatile("s_waitcnt vmcnt(" #n ")" ::: "memory")
; #define PG8_WAIT_L(n) asm volatile("s_waitcnt lgkmcnt(" #n ")" ::: "memory")
; template <class Epi, class Sched, bool ALIGN_EPI = false, bool SP2 = false, bool KHOOK = false>
; __device__ __forceinline__ void gemm_phase(PG8_LAS unsigned char* lds, const Gemm g, const Sched& S, const Epi& E, const int tid_in) {
;     ...
;         for (int t = 0; t < nt; t += 2) {
;             const bool last = (t == nt - 2);
;             const char* a1 = cA + (size_t)(t + 1) * kstep;
;             const char* a2 = last ? nA : cA + (size_t)(t + 2) * kstep; const char* b2 = last ? nB : cB + (size_t)(t + 2) * kstep;
;             const char* a3 = a2 + kstep; const char* b3 = b2 + kstep;
;             if (last && has_next) S.a_ready(nxt);
;             if constexpr (SP2) {
;             PG8_LDB(B0, 0, 0); PG8_LDB(B1, 0, 1); PG8_SCHED; PG8_LDA(At, 0, 0); PG8_STAGE(PG8_SA(1, 1), a1 + hstep, voffA);
;             PG8_WAIT_V(8); PG8_WAIT_L(0); PG8_BAR; PG8_MMA(0, 0, At, B0); PG8_MMA(0, 1, At, B1); PG8_BAR; PG8_SCHED;
;             PG8_LDA(At, 0, 1); PG8_STAGE(PG8_SB(0, 0), b2, voffB); PG8_STAGE(PG8_SB(0, 1), b2 + hstep, voffB); PG8_STAGE(PG8_SA(0, 0), a2, voffA);
;             PG8_WAIT_V(8); PG8_WAIT_L(0); PG8_BAR; PG8_MMA(1, 0, At, B0); PG8_MMA(1, 1, At, B1); PG8_BAR; PG8_SCHED;
;             PG8_LDB(B0, 1, 0); PG8_LDB(B1, 1, 1); PG8_SCHED; PG8_LDA(At, 1, 0); PG8_STAGE(PG8_SA(0, 1), a2 + hstep, voffA);
;             PG8_WAIT_V(8); PG8_WAIT_L(0); PG8_BAR; PG8_MMA(0, 0, At, B0); PG8_MMA(0, 1, At, B1); PG8_BAR; PG8_SCHED;
;             PG8_LDA(At, 1, 1); PG8_STAGE(PG8_SB(1, 0), b3, voffB); PG8_STAGE(PG8_SB(1, 1), b3 + hstep, voffB); PG8_STAGE(PG8_SA(1, 0), a3, voffA);
;             PG8_WAIT_V(8); PG8_WAIT_L(0); PG8_BAR; PG8_MMA(1, 0, At, B0); PG8_MMA(1, 1, At, B1); PG8_BAR; PG8_SCHED;
	s_add_i32 s47, s47, s33
	v_lshl_add_u64 v[192:193], v[192:193], 0, s[90:91]
	s_mov_b32 m0, s47
	ds_read_b128 v[172:175], v139 offset:49152
	ds_read_b128 v[176:179], v139 offset:50176
	ds_read_b128 v[180:183], v139 offset:51200
	ds_read_b128 v[184:187], v139 offset:52224
	ds_read_b128 v[188:191], v139 offset:53248
	ds_read_b128 v[198:201], v139 offset:54272
	ds_read_b128 v[202:205], v139 offset:55296
	ds_read_b128 v[206:209], v139 offset:56320
	global_load_lds_dwordx4 v[192:193], off
	s_add_i32 m0, s47, 0x2000
	s_add_u32 s30, s30, 0x80080
	v_lshl_add_u64 v[192:193], v[210:211], 0, s[90:91]
	s_addc_u32 s31, s31, 0
	s_add_i32 s47, s50, s33
	global_load_lds_dwordx4 v[192:193], off
	v_lshl_add_u64 v[192:193], s[30:31], 0, v[32:33]
	s_mov_b32 m0, s47
	s_nop 0
	global_load_lds_dwordx4 v[192:193], off
	v_lshl_add_u64 v[192:193], s[30:31], 0, v[130:131]
	s_add_i32 m0, s47, 0x2000
	s_nop 0
	global_load_lds_dwordx4 v[192:193], off
	v_lshl_add_u64 v[192:193], v[212:213], 0, s[90:91]
	s_mov_b32 m0, s40
	s_nop 0
	global_load_lds_dwordx4 v[192:193], off
	v_lshl_add_u64 v[192:193], v[214:215], 0, s[90:91]
	s_mov_b32 m0, s41
	s_nop 0
	global_load_lds_dwordx4 v[192:193], off
	s_waitcnt vmcnt(8)
	s_waitcnt lgkmcnt(0)
	s_barrier
	s_setprio 1
	s_waitcnt lgkmcnt(0)
	v_mfma_f32_16x16x32_bf16 v[62:65], v[140:143], v[172:175], v[62:65]
	v_mfma_f32_16x16x32_bf16 v[58:61], v[148:151], v[172:175], v[58:61]
	v_mfma_f32_16x16x32_bf16 v[46:49], v[140:143], v[180:183], v[46:49]
	v_mfma_f32_16x16x32_bf16 v[42:45], v[148:151], v[180:183], v[42:45]
	v_mfma_f32_16x16x32_bf16 v[28:31], v[140:143], v[188:191], v[28:31]
	v_mfma_f32_16x16x32_bf16 v[24:27], v[148:151], v[188:191], v[24:27]
	v_mfma_f32_16x16x32_bf16 v[12:15], v[140:143], v[202:205], v[12:15]
	v_mfma_f32_16x16x32_bf16 v[8:11], v[148:151], v[202:205], v[8:11]
	v_mfma_f32_16x16x32_bf16 v[62:65], v[144:147], v[176:179], v[62:65]
	v_mfma_f32_16x16x32_bf16 v[58:61], v[152:155], v[176:179], v[58:61]
	v_mfma_f32_16x16x32_bf16 v[46:49], v[144:147], v[184:187], v[46:49]
	v_mfma_f32_16x16x32_bf16 v[42:45], v[152:155], v[184:187], v[42:45]
	v_mfma_f32_16x16x32_bf16 v[28:31], v[144:147], v[198:201], v[28:31]
	v_mfma_f32_16x16x32_bf16 v[24:27], v[152:155], v[198:201], v[24:27]
	v_mfma_f32_16x16x32_bf16 v[12:15], v[144:147], v[206:209], v[12:15]
	v_mfma_f32_16x16x32_bf16 v[8:11], v[152:155], v[206:209], v[8:11]
	s_setprio 0
	s_setprio 1
	v_mfma_f32_16x16x32_bf16 v[54:57], v[156:159], v[172:175], v[54:57]
	v_mfma_f32_16x16x32_bf16 v[50:53], v[164:167], v[172:175], v[50:53]
	v_mfma_f32_16x16x32_bf16 v[38:41], v[156:159], v[180:183], v[38:41]
	v_mfma_f32_16x16x32_bf16 v[34:37], v[164:167], v[180:183], v[34:37]
	v_mfma_f32_16x16x32_bf16 v[20:23], v[156:159], v[188:191], v[20:23]
	v_mfma_f32_16x16x32_bf16 v[16:19], v[164:167], v[188:191], v[16:19]
	v_mfma_f32_16x16x32_bf16 v[4:7], v[156:159], v[202:205], v[4:7]
	v_mfma_f32_16x16x32_bf16 v[0:3], v[164:167], v[202:205], v[0:3]
	v_mfma_f32_16x16x32_bf16 v[54:57], v[160:163], v[176:179], v[54:57]
	v_mfma_f32_16x16x32_bf16 v[50:53], v[168:171], v[176:179], v[50:53]
	v_mfma_f32_16x16x32_bf16 v[38:41], v[160:163], v[184:187], v[38:41]
	v_mfma_f32_16x16x32_bf16 v[34:37], v[168:171], v[184:187], v[34:37]
	v_mfma_f32_16x16x32_bf16 v[20:23], v[160:163], v[198:201], v[20:23]
	v_mfma_f32_16x16x32_bf16 v[16:19], v[168:171], v[198:201], v[16:19]
	v_mfma_f32_16x16x32_bf16 v[4:7], v[160:163], v[206:209], v[4:7]
	v_mfma_f32_16x16x32_bf16 v[0:3], v[168:171], v[206:209], v[0:3]
	s_setprio 0
	s_barrier
	s_add_i32 s46, s46, 2
	s_add_u32 s26, s26, 0x100
	s_addc_u32 s27, s27, 0
	s_add_u32 s44, s44, 0x100
	s_addc_u32 s45, s45, 0
	s_cmp_lg_u32 s46, 28
	s_cbranch_scc1 .Lg4_cont
	s_cmp_lg_u64 s[14:15], 0
	s_cbranch_scc1 .Lg4_last
.Lg4_cont:
	s_cmp_gt_u32 s46, 29
	s_cbranch_scc0 .LBB0_1063
	s_branch .Lg4_kexit
.Lg4_last:
	s_add_u32 s30, s26, 0xfff80080
	s_addc_u32 s31, s27, -1
	s_add_i32 s47, 0, 0x10000
	s_cmp_eq_u32 s46, 28
	s_cselect_b32 s49, s13, s31
	s_cselect_b32 s48, s24, s30
	s_cselect_b32 s31, s11, s45
	s_cselect_b32 s30, s25, s44
	s_add_i32 s52, 0, 0x14000
	v_add_u32_e32 v152, s47, v137
	v_add_u32_e32 v168, s52, v137
	ds_read_b128 v[140:143], v152
	ds_read_b128 v[144:147], v152 offset:1024
	ds_read_b128 v[148:151], v152 offset:2048
	ds_read_b128 v[152:155], v152 offset:3072
	ds_read_b128 v[156:159], v168
	ds_read_b128 v[160:163], v168 offset:1024
	ds_read_b128 v[164:167], v168 offset:2048
	ds_read_b128 v[168:171], v168 offset:3072
	v_lshl_add_u64 v[192:193], s[26:27], 0, v[132:133]
	s_add_i32 m0, s36, 0xc000
	ds_read_b128 v[172:175], v139
	ds_read_b128 v[176:179], v139 offset:1024
	ds_read_b128 v[180:183], v139 offset:2048
	ds_read_b128 v[184:187], v139 offset:3072
	ds_read_b128 v[188:191], v139 offset:4096
	ds_read_b128 v[198:201], v139 offset:5120
	ds_read_b128 v[202:205], v139 offset:6144
	ds_read_b128 v[206:209], v139 offset:7168
	global_load_lds_dwordx4 v[192:193], off
	v_lshl_add_u64 v[192:193], s[26:27], 0, v[134:135]
	s_add_i32 m0, s36, 0xe000
	s_nop 0
	global_load_lds_dwordx4 v[192:193], off
	s_waitcnt vmcnt(8)
	s_waitcnt lgkmcnt(0)
	s_barrier
; #define PG8_STAGE(bufoff, gbase, voff) do { _Pragma("unroll") for (int _i = 0; _i < 2; ++_i) \
;         __builtin_amdgcn_global_load_lds((const unsigned*)((const char*)(gbase) + (voff)[_i]), (PG8_LAS unsigned*)(lds + (bufoff) + ldsw + _i * 8192), 16, 0, 0); } while (0)
; #define PG8_LDA(dst, b, h) do { _Pragma("unroll") for (int m = 0; m < 4; ++m) _Pragma("unroll") for (int k = 0; k < 2; ++k) dst[m][k] = *(const PG8_LAS bf16x8*)(lds + PG8_SA(b, h) + aoff + m * 2048 + k * 1024); } while (0)
; #define PG8_MMA(ai, bj, At, Bt) do { __builtin_amdgcn_s_setprio(1); _Pragma("unroll") for (int m = 0; m < 4; ++m) _Pragma("unroll") for (int n = 0; n < 2; ++n) _Pragma("unroll") for (int k = 0; k < 2; ++k) \
;         acc[ai][bj][m][n] = __builtin_amdgcn_mfma_f32_16x16x32_bf16(Bt[n][k], At[m][k], acc[ai][bj][m][n], 0, 0, 0); __builtin_amdgcn_s_setprio(0); } while (0)
; #define PG8_WAIT_V(n) asm volatile("s_waitcnt vmcnt(" #n ")" ::: "memory")
; #define PG8_WAIT_L(n) asm volatile("s_waitcnt lgkmcnt(" #n ")" ::: "memory")
; #define PG8_BAR __builtin_amdgcn_s_barrier()
; #define PG8_SCHED __builtin_amdgcn_sched_barrier(0)
; template <class Epi, class Sched, bool ALIGN_EPI = false, bool SP2 = false, bool KHOOK = false>
; __device__ __forceinline__ void gemm_phase(PG8_LAS unsigned char* lds, const Gemm g, const Sched& S, const Epi& E, const int tid_in) {
;     ...
;             PG8_WAIT_V(8); PG8_WAIT_L(0); PG8_BAR; PG8_MMA(0, 0, At, B0); PG8_MMA(0, 1, At, B1); PG8_BAR; PG8_SCHED;
;             PG8_LDA(At, 0, 1); PG8_STAGE(PG8_SB(0, 0), b2, voffB); PG8_STAGE(PG8_SB(0, 1), b2 + hstep, voffB); PG8_STAGE(PG8_SA(0, 0), a2, voffA);
;             PG8_WAIT_V(8); PG8_WAIT_L(0); PG8_BAR; PG8_MMA(1, 0, At, B0); PG8_MMA(1, 1, At, B1); PG8_BAR; PG8_SCHED;
	s_setprio 1
	s_waitcnt lgkmcnt(0)
	v_mfma_f32_16x16x32_bf16 v[126:129], v[140:143], v[172:175], v[126:129]
	v_mfma_f32_16x16x32_bf16 v[122:125], v[148:151], v[172:175], v[122:125]
	v_mfma_f32_16x16x32_bf16 v[110:113], v[140:143], v[180:183], v[110:113]
	v_mfma_f32_16x16x32_bf16 v[106:109], v[148:151], v[180:183], v[106:109]
	v_mfma_f32_16x16x32_bf16 v[94:97], v[140:143], v[188:191], v[94:97]
	v_mfma_f32_16x16x32_bf16 v[90:93], v[148:151], v[188:191], v[90:93]
	v_mfma_f32_16x16x32_bf16 v[78:81], v[140:143], v[202:205], v[78:81]
	v_mfma_f32_16x16x32_bf16 v[74:77], v[148:151], v[202:205], v[74:77]
	v_mfma_f32_16x16x32_bf16 v[126:129], v[144:147], v[176:179], v[126:129]
	v_mfma_f32_16x16x32_bf16 v[122:125], v[152:155], v[176:179], v[122:125]
	v_mfma_f32_16x16x32_bf16 v[110:113], v[144:147], v[184:187], v[110:113]
	v_mfma_f32_16x16x32_bf16 v[106:109], v[152:155], v[184:187], v[106:109]
	v_mfma_f32_16x16x32_bf16 v[94:97], v[144:147], v[198:201], v[94:97]
	v_mfma_f32_16x16x32_bf16 v[90:93], v[152:155], v[198:201], v[90:93]
	v_mfma_f32_16x16x32_bf16 v[78:81], v[144:147], v[206:209], v[78:81]
	v_mfma_f32_16x16x32_bf16 v[74:77], v[152:155], v[206:209], v[74:77]
	s_setprio 0
	s_setprio 1
	v_mfma_f32_16x16x32_bf16 v[118:121], v[156:159], v[172:175], v[118:121]
	v_mfma_f32_16x16x32_bf16 v[114:117], v[164:167], v[172:175], v[114:117]
	v_mfma_f32_16x16x32_bf16 v[102:105], v[156:159], v[180:183], v[102:105]
	v_mfma_f32_16x16x32_bf16 v[98:101], v[164:167], v[180:183], v[98:101]
	v_mfma_f32_16x16x32_bf16 v[86:89], v[156:159], v[188:191], v[86:89]
	v_mfma_f32_16x16x32_bf16 v[82:85], v[164:167], v[188:191], v[82:85]
	v_mfma_f32_16x16x32_bf16 v[70:73], v[156:159], v[202:205], v[70:73]
	v_mfma_f32_16x16x32_bf16 v[66:69], v[164:167], v[202:205], v[66:69]
	v_mfma_f32_16x16x32_bf16 v[118:121], v[160:163], v[176:179], v[118:121]
	v_mfma_f32_16x16x32_bf16 v[114:117], v[168:171], v[176:179], v[114:117]
	v_mfma_f32_16x16x32_bf16 v[102:105], v[160:163], v[184:187], v[102:105]
	v_mfma_f32_16x16x32_bf16 v[98:101], v[168:171], v[184:187], v[98:101]
	v_mfma_f32_16x16x32_bf16 v[86:89], v[160:163], v[198:201], v[86:89]
	v_mfma_f32_16x16x32_bf16 v[82:85], v[168:171], v[198:201], v[82:85]
	v_mfma_f32_16x16x32_bf16 v[70:73], v[160:163], v[206:209], v[70:73]
	v_mfma_f32_16x16x32_bf16 v[66:69], v[168:171], v[206:209], v[66:69]
	s_setprio 0
	s_barrier
	s_add_i32 s47, s47, s33
	v_lshl_add_u64 v[192:193], s[30:31], 0, v[32:33]
	s_mov_b32 m0, s47
	ds_read_b128 v[172:175], v139 offset:16384
	ds_read_b128 v[176:179], v139 offset:17408
	ds_read_b128 v[180:183], v139 offset:18432
	ds_read_b128 v[184:187], v139 offset:19456
	ds_read_b128 v[188:191], v139 offset:20480
	ds_read_b128 v[198:201], v139 offset:21504
	ds_read_b128 v[202:205], v139 offset:22528
	ds_read_b128 v[206:209], v139 offset:23552
	global_load_lds_dwordx4 v[192:193], off
	s_add_i32 m0, s47, 0x2000
	s_add_u32 s50, s30, 0x80000
	v_lshl_add_u64 v[210:211], s[30:31], 0, v[130:131]
	s_addc_u32 s51, s31, 0
	s_add_i32 s47, s52, s33
	global_load_lds_dwordx4 v[210:211], off
	v_lshl_add_u64 v[212:213], s[50:51], 0, v[32:33]
	s_mov_b32 m0, s47
	v_lshl_add_u64 v[214:215], s[48:49], 0, v[130:131]
	global_load_lds_dwordx4 v[212:213], off
	v_lshl_add_u64 v[212:213], s[50:51], 0, v[130:131]
	s_add_i32 m0, s47, 0x2000
	s_nop 0
	global_load_lds_dwordx4 v[212:213], off
	v_lshl_add_u64 v[212:213], s[48:49], 0, v[32:33]
	s_mov_b32 m0, s36
	s_nop 0
	global_load_lds_dwordx4 v[212:213], off
	s_mov_b32 m0, s37
	s_nop 0
	global_load_lds_dwordx4 v[214:215], off
	s_waitcnt vmcnt(8)
	s_waitcnt lgkmcnt(0)
	s_barrier
	s_setprio 1
	s_waitcnt lgkmcnt(0)
	v_mfma_f32_16x16x32_bf16 v[62:65], v[140:143], v[172:175], v[62:65]
	v_mfma_f32_16x16x32_bf16 v[58:61], v[148:151], v[172:175], v[58:61]
	v_mfma_f32_16x16x32_bf16 v[46:49], v[140:143], v[180:183], v[46:49]
	v_mfma_f32_16x16x32_bf16 v[42:45], v[148:151], v[180:183], v[42:45]
	v_mfma_f32_16x16x32_bf16 v[28:31], v[140:143], v[188:191], v[28:31]
	v_mfma_f32_16x16x32_bf16 v[24:27], v[148:151], v[188:191], v[24:27]
	v_mfma_f32_16x16x32_bf16 v[12:15], v[140:143], v[202:205], v[12:15]
	v_mfma_f32_16x16x32_bf16 v[8:11], v[148:151], v[202:205], v[8:11]
	v_mfma_f32_16x16x32_bf16 v[62:65], v[144:147], v[176:179], v[62:65]
	v_mfma_f32_16x16x32_bf16 v[58:61], v[152:155], v[176:179], v[58:61]
	v_mfma_f32_16x16x32_bf16 v[46:49], v[144:147], v[184:187], v[46:49]
	v_mfma_f32_16x16x32_bf16 v[42:45], v[152:155], v[184:187], v[42:45]
	v_mfma_f32_16x16x32_bf16 v[28:31], v[144:147], v[198:201], v[28:31]
	v_mfma_f32_16x16x32_bf16 v[24:27], v[152:155], v[198:201], v[24:27]
	v_mfma_f32_16x16x32_bf16 v[12:15], v[144:147], v[206:209], v[12:15]
	v_mfma_f32_16x16x32_bf16 v[8:11], v[152:155], v[206:209], v[8:11]
	s_setprio 0
	s_setprio 1
	v_mfma_f32_16x16x32_bf16 v[54:57], v[156:159], v[172:175], v[54:57]
	v_mfma_f32_16x16x32_bf16 v[50:53], v[164:167], v[172:175], v[50:53]
	v_mfma_f32_16x16x32_bf16 v[38:41], v[156:159], v[180:183], v[38:41]
	v_mfma_f32_16x16x32_bf16 v[34:37], v[164:167], v[180:183], v[34:37]
	v_mfma_f32_16x16x32_bf16 v[20:23], v[156:159], v[188:191], v[20:23]
	v_mfma_f32_16x16x32_bf16 v[16:19], v[164:167], v[188:191], v[16:19]
	v_mfma_f32_16x16x32_bf16 v[4:7], v[156:159], v[202:205], v[4:7]
	v_mfma_f32_16x16x32_bf16 v[0:3], v[164:167], v[202:205], v[0:3]
	v_mfma_f32_16x16x32_bf16 v[54:57], v[160:163], v[176:179], v[54:57]
	v_mfma_f32_16x16x32_bf16 v[50:53], v[168:171], v[176:179], v[50:53]
	v_mfma_f32_16x16x32_bf16 v[38:41], v[160:163], v[184:187], v[38:41]
	v_mfma_f32_16x16x32_bf16 v[34:37], v[168:171], v[184:187], v[34:37]
	v_mfma_f32_16x16x32_bf16 v[20:23], v[160:163], v[198:201], v[20:23]
	v_mfma_f32_16x16x32_bf16 v[16:19], v[168:171], v[198:201], v[16:19]
	v_mfma_f32_16x16x32_bf16 v[4:7], v[160:163], v[206:209], v[4:7]
	v_mfma_f32_16x16x32_bf16 v[0:3], v[168:171], v[206:209], v[0:3]
	s_setprio 0
	s_barrier
; __device__ __forceinline__ unsigned cvt_pk_bf16(float lo, float hi) { const f32x2_t v = {lo, hi}; const bf16x2_t c = __builtin_convertvector(v, bf16x2_t); return __builtin_bit_cast(unsigned, c); }
; __device__ __forceinline__ float siluf_fast(float x) { return x * sigmoidf_fast(x); }
; #define PG8_STAGE(bufoff, gbase, voff) do { _Pragma("unroll") for (int _i = 0; _i < 2; ++_i) \
;         __builtin_amdgcn_global_load_lds((const unsigned*)((const char*)(gbase) + (voff)[_i]), (PG8_LAS unsigned*)(lds + (bufoff) + ldsw + _i * 8192), 16, 0, 0); } while (0)
; #define PG8_LDA(dst, b, h) do { _Pragma("unroll") for (int m = 0; m < 4; ++m) _Pragma("unroll") for (int k = 0; k < 2; ++k) dst[m][k] = *(const PG8_LAS bf16x8*)(lds + PG8_SA(b, h) + aoff + m * 2048 + k * 1024); } while (0)
; #define PG8_BAR __builtin_amdgcn_s_barrier()
;     __device__ __forceinline__ void operator()(const f32x4 (&acc)[2][2][4][2], const Unit& u, int wr, int wc, int fr, int fq) const {
;         const int row0 = u.pm * BM + wr * 64 + fr, col0 = u.pn * HALF + wc * 32 + 8 * fq;
; #pragma unroll
;         for (int ai = 0; ai < 2; ++ai)
; #pragma unroll
;             for (int m = 0; m < 4; ++m) { const size_t r = (size_t)(row0 + ai * HALF + m * 16);
;                 const f32x4 g0 = acc[ai][0][m][0], u0 = acc[ai][0][m][1], g1 = acc[ai][1][m][0], u1 = acc[ai][1][m][1];
;                 u32x4 w; w.x = cvt_pk_bf16(siluf_fast(g0[0]) * u0[0], siluf_fast(g0[1]) * u0[1]); w.y = cvt_pk_bf16(siluf_fast(g0[2]) * u0[2], siluf_fast(g0[3]) * u0[3]);
;                 w.z = cvt_pk_bf16(siluf_fast(g1[0]) * u1[0], siluf_fast(g1[1]) * u1[1]); w.w = cvt_pk_bf16(siluf_fast(g1[2]) * u1[2], siluf_fast(g1[3]) * u1[3]);
;                 *(u32x4*)(O + r * ldo + col0) = w; }
; template <class Epi, class Sched, bool ALIGN_EPI = false, bool SP2 = false, bool KHOOK = false>
; __device__ __forceinline__ void gemm_phase(PG8_LAS unsigned char* lds, const Gemm g, const Sched& S, const Epi& E, const int tid_in) {
;     ...
;             PG8_LDB(B0, 1, 0); PG8_LDB(B1, 1, 1); PG8_SCHED; PG8_LDA(At, 1, 0); PG8_STAGE(PG8_SA(0, 1), a2 + hstep, voffA);
;             PG8_WAIT_V(8); PG8_WAIT_L(0); PG8_BAR; PG8_MMA(0, 0, At, B0); PG8_MMA(0, 1, At, B1); PG8_BAR; PG8_SCHED;
;             PG8_LDA(At, 1, 1); PG8_STAGE(PG8_SB(1, 0), b3, voffB); PG8_STAGE(PG8_SB(1, 1), b3 + hstep, voffB); PG8_STAGE(PG8_SA(1, 0), a3, voffA);
	s_add_i32 s47, 0, 0x18000
	s_add_i32 s50, 0, 0x1c000
	v_add_u32_e32 v152, s47, v137
	v_add_u32_e32 v168, s50, v137
	ds_read_b128 v[140:143], v152
	ds_read_b128 v[144:147], v152 offset:1024
	ds_read_b128 v[148:151], v152 offset:2048
	ds_read_b128 v[152:155], v152 offset:3072
	ds_read_b128 v[156:159], v168
	ds_read_b128 v[160:163], v168 offset:1024
	ds_read_b128 v[164:167], v168 offset:2048
	ds_read_b128 v[168:171], v168 offset:3072
	s_add_u32 s48, s48, 0x80000
	s_addc_u32 s49, s49, 0
	s_mov_b32 m0, s38
	v_lshl_add_u64 v[216:217], s[48:49], 0, v[32:33]
	ds_read_b128 v[172:175], v139 offset:32768
	ds_read_b128 v[176:179], v139 offset:33792
	ds_read_b128 v[180:183], v139 offset:34816
	ds_read_b128 v[184:187], v139 offset:35840
	ds_read_b128 v[188:191], v139 offset:36864
	ds_read_b128 v[198:201], v139 offset:37888
	ds_read_b128 v[202:205], v139 offset:38912
	ds_read_b128 v[206:209], v139 offset:39936
	global_load_lds_dwordx4 v[216:217], off
	v_lshl_add_u64 v[216:217], s[48:49], 0, v[130:131]
	s_mov_b32 m0, s39
	s_nop 0
	global_load_lds_dwordx4 v[216:217], off
	s_waitcnt vmcnt(8)
	s_waitcnt lgkmcnt(0)
	s_barrier
	s_setprio 1
	s_waitcnt lgkmcnt(0)
	v_mfma_f32_16x16x32_bf16 v[126:129], v[140:143], v[172:175], v[126:129]
	v_mfma_f32_16x16x32_bf16 v[122:125], v[148:151], v[172:175], v[122:125]
	v_mfma_f32_16x16x32_bf16 v[110:113], v[140:143], v[180:183], v[110:113]
	v_mfma_f32_16x16x32_bf16 v[106:109], v[148:151], v[180:183], v[106:109]
	v_mfma_f32_16x16x32_bf16 v[94:97], v[140:143], v[188:191], v[94:97]
	v_mfma_f32_16x16x32_bf16 v[90:93], v[148:151], v[188:191], v[90:93]
	v_mfma_f32_16x16x32_bf16 v[78:81], v[140:143], v[202:205], v[78:81]
	v_mfma_f32_16x16x32_bf16 v[74:77], v[148:151], v[202:205], v[74:77]
	v_mfma_f32_16x16x32_bf16 v[126:129], v[144:147], v[176:179], v[126:129]
	v_mfma_f32_16x16x32_bf16 v[122:125], v[152:155], v[176:179], v[122:125]
	v_mfma_f32_16x16x32_bf16 v[110:113], v[144:147], v[184:187], v[110:113]
	v_mfma_f32_16x16x32_bf16 v[106:109], v[152:155], v[184:187], v[106:109]
	v_mfma_f32_16x16x32_bf16 v[94:97], v[144:147], v[198:201], v[94:97]
	v_mfma_f32_16x16x32_bf16 v[90:93], v[152:155], v[198:201], v[90:93]
	v_mfma_f32_16x16x32_bf16 v[78:81], v[144:147], v[206:209], v[78:81]
	v_mfma_f32_16x16x32_bf16 v[74:77], v[152:155], v[206:209], v[74:77]
	s_setprio 0
	s_setprio 1
	v_mfma_f32_16x16x32_bf16 v[118:121], v[156:159], v[172:175], v[118:121]
	v_mfma_f32_16x16x32_bf16 v[114:117], v[164:167], v[172:175], v[114:117]
	v_mfma_f32_16x16x32_bf16 v[102:105], v[156:159], v[180:183], v[102:105]
	v_mfma_f32_16x16x32_bf16 v[98:101], v[164:167], v[180:183], v[98:101]
	v_mfma_f32_16x16x32_bf16 v[86:89], v[156:159], v[188:191], v[86:89]
	v_mfma_f32_16x16x32_bf16 v[82:85], v[164:167], v[188:191], v[82:85]
	v_mfma_f32_16x16x32_bf16 v[70:73], v[156:159], v[202:205], v[70:73]
	v_mfma_f32_16x16x32_bf16 v[66:69], v[164:167], v[202:205], v[66:69]
	v_mfma_f32_16x16x32_bf16 v[118:121], v[160:163], v[176:179], v[118:121]
	v_mfma_f32_16x16x32_bf16 v[114:117], v[168:171], v[176:179], v[114:117]
	v_mfma_f32_16x16x32_bf16 v[102:105], v[160:163], v[184:187], v[102:105]
	v_mfma_f32_16x16x32_bf16 v[98:101], v[168:171], v[184:187], v[98:101]
	v_mfma_f32_16x16x32_bf16 v[86:89], v[160:163], v[198:201], v[86:89]
	v_mfma_f32_16x16x32_bf16 v[82:85], v[168:171], v[198:201], v[82:85]
	v_mfma_f32_16x16x32_bf16 v[70:73], v[160:163], v[206:209], v[70:73]
	v_mfma_f32_16x16x32_bf16 v[66:69], v[168:171], v[206:209], v[66:69]
	s_setprio 0
	s_barrier
	s_add_i32 s47, s47, s33
	v_lshl_add_u64 v[192:193], v[192:193], 0, s[90:91]
	s_mov_b32 m0, s47
	ds_read_b128 v[172:175], v139 offset:49152
	ds_read_b128 v[176:179], v139 offset:50176
	ds_read_b128 v[180:183], v139 offset:51200
	ds_read_b128 v[184:187], v139 offset:52224
	ds_read_b128 v[188:191], v139 offset:53248
	ds_read_b128 v[198:201], v139 offset:54272
	ds_read_b128 v[202:205], v139 offset:55296
	ds_read_b128 v[206:209], v139 offset:56320
	global_load_lds_dwordx4 v[192:193], off
	s_add_i32 m0, s47, 0x2000
	s_add_u32 s30, s30, 0x80080
	v_lshl_add_u64 v[192:193], v[210:211], 0, s[90:91]
	s_addc_u32 s31, s31, 0
	s_add_i32 s47, s50, s33
	global_load_lds_dwordx4 v[192:193], off
	v_lshl_add_u64 v[192:193], s[30:31], 0, v[32:33]
	s_mov_b32 m0, s47
	s_nop 0
	global_load_lds_dwordx4 v[192:193], off
	v_lshl_add_u64 v[192:193], s[30:31], 0, v[130:131]
	s_add_i32 m0, s47, 0x2000
	s_nop 0
	global_load_lds_dwordx4 v[192:193], off
	v_lshl_add_u64 v[192:193], v[212:213], 0, s[90:91]
	s_mov_b32 m0, s40
	s_nop 0
	global_load_lds_dwordx4 v[192:193], off
	v_lshl_add_u64 v[192:193], v[214:215], 0, s[90:91]
	s_mov_b32 m0, s41
	s_nop 0
	global_load_lds_dwordx4 v[192:193], off
	s_mov_b32 s56, 0x2c000
	s_mov_b32 s57, 0
	s_mov_b32 s58, 0xdc000
	s_mov_b32 s59, 0
	v_lshl_add_u32 v246, s18, 8, v136
	v_lshl_or_b32 v222, s19, 7, v138
	v_lshlrev_b32_e32 v222, 1, v222
	v_mov_b32_e32 v223, 0
	s_movk_i32 s64, 0x2c00
	v_readlane_b32 s68, v254, 28
	v_readlane_b32 s69, v254, 29
	v_mad_u64_u32 v[248:249], s[70:71], v246, s64, v[222:223]
	v_lshl_add_u64 v[248:249], v[248:249], 0, s[68:69]
	v_mul_f32_e32 v218, 0xbfb8aa3b, v126
	v_mul_f32_e32 v219, 0xbfb8aa3b, v127
	v_mul_f32_e32 v220, 0xbfb8aa3b, v128
	v_mul_f32_e32 v221, 0xbfb8aa3b, v129
	v_exp_f32_e32 v218, v218
	v_exp_f32_e32 v219, v219
	v_exp_f32_e32 v220, v220
	v_exp_f32_e32 v221, v221
	v_add_f32_e32 v218, 1.0, v218
	v_add_f32_e32 v219, 1.0, v219
	v_add_f32_e32 v220, 1.0, v220
	v_add_f32_e32 v221, 1.0, v221
	v_rcp_f32_e32 v218, v218
	v_rcp_f32_e32 v219, v219
	v_rcp_f32_e32 v220, v220
	v_rcp_f32_e32 v221, v221
	v_mul_f32_e32 v126, v126, v218
	v_mul_f32_e32 v127, v127, v219
	v_mul_f32_e32 v128, v128, v220
; __device__ __forceinline__ unsigned cvt_pk_bf16(float lo, float hi) { const f32x2_t v = {lo, hi}; const bf16x2_t c = __builtin_convertvector(v, bf16x2_t); return __builtin_bit_cast(unsigned, c); }
; __device__ __forceinline__ float siluf_fast(float x) { return x * sigmoidf_fast(x); }
; #define PG8_MMA(ai, bj, At, Bt) do { __builtin_amdgcn_s_setprio(1); _Pragma("unroll") for (int m = 0; m < 4; ++m) _Pragma("unroll") for (int n = 0; n < 2; ++n) _Pragma("unroll") for (int k = 0; k < 2; ++k) \
;         acc[ai][bj][m][n] = __builtin_amdgcn_mfma_f32_16x16x32_bf16(Bt[n][k], At[m][k], acc[ai][bj][m][n], 0, 0, 0); __builtin_amdgcn_s_setprio(0); } while (0)
; #define PG8_WAIT_V(n) asm volatile("s_waitcnt vmcnt(" #n ")" ::: "memory")
; #define PG8_WAIT_L(n) asm volatile("s_waitcnt lgkmcnt(" #n ")" ::: "memory")
; #define PG8_BAR __builtin_amdgcn_s_barrier()
; #define PG8_SCHED __builtin_amdgcn_sched_barrier(0)
;     __device__ __forceinline__ void operator()(const f32x4 (&acc)[2][2][4][2], const Unit& u, int wr, int wc, int fr, int fq) const {
;         const int row0 = u.pm * BM + wr * 64 + fr, col0 = u.pn * HALF + wc * 32 + 8 * fq;
; #pragma unroll
;         for (int ai = 0; ai < 2; ++ai)
; #pragma unroll
;             for (int m = 0; m < 4; ++m) { const size_t r = (size_t)(row0 + ai * HALF + m * 16);
;                 const f32x4 g0 = acc[ai][0][m][0], u0 = acc[ai][0][m][1], g1 = acc[ai][1][m][0], u1 = acc[ai][1][m][1];
;                 u32x4 w; w.x = cvt_pk_bf16(siluf_fast(g0[0]) * u0[0], siluf_fast(g0[1]) * u0[1]); w.y = cvt_pk_bf16(siluf_fast(g0[2]) * u0[2], siluf_fast(g0[3]) * u0[3]);
;                 w.z = cvt_pk_bf16(siluf_fast(g1[0]) * u1[0], siluf_fast(g1[1]) * u1[1]); w.w = cvt_pk_bf16(siluf_fast(g1[2]) * u1[2], siluf_fast(g1[3]) * u1[3]);
;                 *(u32x4*)(O + r * ldo + col0) = w; }
; template <class Epi, class Sched, bool ALIGN_EPI = false, bool SP2 = false, bool KHOOK = false>
; __device__ __forceinline__ void gemm_phase(PG8_LAS unsigned char* lds, const Gemm g, const Sched& S, const Epi& E, const int tid_in) {
;     ...
;             PG8_WAIT_V(8); PG8_WAIT_L(0); PG8_BAR; PG8_MMA(1, 0, At, B0); PG8_MMA(1, 1, At, B1); PG8_BAR; PG8_SCHED;
	v_mul_f32_e32 v129, v129, v221
	v_mul_f32_e32 v122, v122, v126
	v_mul_f32_e32 v123, v123, v127
	v_mul_f32_e32 v124, v124, v128
	v_mul_f32_e32 v125, v125, v129
	v_mul_f32_e32 v218, 0xbfb8aa3b, v118
	v_mul_f32_e32 v219, 0xbfb8aa3b, v119
	v_mul_f32_e32 v220, 0xbfb8aa3b, v120
	v_mul_f32_e32 v221, 0xbfb8aa3b, v121
	v_exp_f32_e32 v218, v218
	v_exp_f32_e32 v219, v219
	v_exp_f32_e32 v220, v220
	v_exp_f32_e32 v221, v221
	v_add_f32_e32 v218, 1.0, v218
	v_add_f32_e32 v219, 1.0, v219
	v_add_f32_e32 v220, 1.0, v220
	v_add_f32_e32 v221, 1.0, v221
	v_rcp_f32_e32 v218, v218
	v_rcp_f32_e32 v219, v219
	v_rcp_f32_e32 v220, v220
	v_rcp_f32_e32 v221, v221
	v_mul_f32_e32 v118, v118, v218
	v_mul_f32_e32 v119, v119, v219
	v_mul_f32_e32 v120, v120, v220
	v_mul_f32_e32 v121, v121, v221
	v_mul_f32_e32 v114, v114, v118
	v_mul_f32_e32 v115, v115, v119
	v_mul_f32_e32 v116, v116, v120
	v_mul_f32_e32 v117, v117, v121
	v_cvt_pk_bf16_f32 v122, v122, v123
	v_cvt_pk_bf16_f32 v123, v124, v125
	v_cvt_pk_bf16_f32 v124, v114, v115
	v_cvt_pk_bf16_f32 v125, v116, v117
	global_store_dwordx4 v[248:249], v[122:125], off
	v_lshl_add_u64 v[248:249], v[248:249], 0, s[56:57]
	v_mul_f32_e32 v218, 0xbfb8aa3b, v110
	v_mul_f32_e32 v219, 0xbfb8aa3b, v111
	v_mul_f32_e32 v220, 0xbfb8aa3b, v112
	v_mul_f32_e32 v221, 0xbfb8aa3b, v113
	v_exp_f32_e32 v218, v218
	v_exp_f32_e32 v219, v219
	v_exp_f32_e32 v220, v220
	v_exp_f32_e32 v221, v221
	v_add_f32_e32 v218, 1.0, v218
	v_add_f32_e32 v219, 1.0, v219
	v_add_f32_e32 v220, 1.0, v220
	v_add_f32_e32 v221, 1.0, v221
	v_rcp_f32_e32 v218, v218
	v_rcp_f32_e32 v219, v219
	v_rcp_f32_e32 v220, v220
	v_rcp_f32_e32 v221, v221
	v_mul_f32_e32 v110, v110, v218
	v_mul_f32_e32 v111, v111, v219
	v_mul_f32_e32 v112, v112, v220
	v_mul_f32_e32 v113, v113, v221
	v_mul_f32_e32 v106, v106, v110
	v_mul_f32_e32 v107, v107, v111
	v_mul_f32_e32 v108, v108, v112
	v_mul_f32_e32 v109, v109, v113
	v_mul_f32_e32 v218, 0xbfb8aa3b, v102
	v_mul_f32_e32 v219, 0xbfb8aa3b, v103
	v_mul_f32_e32 v220, 0xbfb8aa3b, v104
	v_mul_f32_e32 v221, 0xbfb8aa3b, v105
	v_exp_f32_e32 v218, v218
	v_exp_f32_e32 v219, v219
	v_exp_f32_e32 v220, v220
	v_exp_f32_e32 v221, v221
	v_add_f32_e32 v218, 1.0, v218
	v_add_f32_e32 v219, 1.0, v219
	v_add_f32_e32 v220, 1.0, v220
	v_add_f32_e32 v221, 1.0, v221
	v_rcp_f32_e32 v218, v218
	v_rcp_f32_e32 v219, v219
	v_rcp_f32_e32 v220, v220
	v_rcp_f32_e32 v221, v221
	v_mul_f32_e32 v102, v102, v218
	v_mul_f32_e32 v103, v103, v219
	v_mul_f32_e32 v104, v104, v220
	v_mul_f32_e32 v105, v105, v221
	v_mul_f32_e32 v98, v98, v102
	v_mul_f32_e32 v99, v99, v103
	v_mul_f32_e32 v100, v100, v104
	v_mul_f32_e32 v101, v101, v105
	v_cvt_pk_bf16_f32 v106, v106, v107
	v_cvt_pk_bf16_f32 v107, v108, v109
	v_cvt_pk_bf16_f32 v108, v98, v99
	v_cvt_pk_bf16_f32 v109, v100, v101
	global_store_dwordx4 v[248:249], v[106:109], off
	v_lshl_add_u64 v[248:249], v[248:249], 0, s[56:57]
	v_mul_f32_e32 v218, 0xbfb8aa3b, v94
	v_mul_f32_e32 v219, 0xbfb8aa3b, v95
	v_mul_f32_e32 v220, 0xbfb8aa3b, v96
	v_mul_f32_e32 v221, 0xbfb8aa3b, v97
	v_exp_f32_e32 v218, v218
	v_exp_f32_e32 v219, v219
	v_exp_f32_e32 v220, v220
	v_exp_f32_e32 v221, v221
	v_add_f32_e32 v218, 1.0, v218
	v_add_f32_e32 v219, 1.0, v219
	v_add_f32_e32 v220, 1.0, v220
	v_add_f32_e32 v221, 1.0, v221
	v_rcp_f32_e32 v218, v218
	v_rcp_f32_e32 v219, v219
	v_rcp_f32_e32 v220, v220
	v_rcp_f32_e32 v221, v221
	v_mul_f32_e32 v94, v94, v218
	v_mul_f32_e32 v95, v95, v219
	v_mul_f32_e32 v96, v96, v220
	v_mul_f32_e32 v97, v97, v221
	v_mul_f32_e32 v90, v90, v94
	v_mul_f32_e32 v91, v91, v95
	v_mul_f32_e32 v92, v92, v96
	v_mul_f32_e32 v93, v93, v97
	v_mul_f32_e32 v218, 0xbfb8aa3b, v86
	v_mul_f32_e32 v219, 0xbfb8aa3b, v87
	v_mul_f32_e32 v220, 0xbfb8aa3b, v88
	v_mul_f32_e32 v221, 0xbfb8aa3b, v89
	v_exp_f32_e32 v218, v218
	v_exp_f32_e32 v219, v219
	v_exp_f32_e32 v220, v220
	v_exp_f32_e32 v221, v221
	v_add_f32_e32 v218, 1.0, v218
	v_add_f32_e32 v219, 1.0, v219
	v_add_f32_e32 v220, 1.0, v220
	v_add_f32_e32 v221, 1.0, v221
	v_rcp_f32_e32 v218, v218
	v_rcp_f32_e32 v219, v219
	v_rcp_f32_e32 v220, v220
	v_rcp_f32_e32 v221, v221
	v_mul_f32_e32 v86, v86, v218
	v_mul_f32_e32 v87, v87, v219
	v_mul_f32_e32 v88, v88, v220
	v_mul_f32_e32 v89, v89, v221
	v_mul_f32_e32 v82, v82, v86
	v_mul_f32_e32 v83, v83, v87
	v_mul_f32_e32 v84, v84, v88
	v_mul_f32_e32 v85, v85, v89
	v_cvt_pk_bf16_f32 v90, v90, v91
	v_cvt_pk_bf16_f32 v91, v92, v93
	v_cvt_pk_bf16_f32 v92, v82, v83
	v_cvt_pk_bf16_f32 v93, v84, v85
	global_store_dwordx4 v[248:249], v[90:93], off
	s_waitcnt vmcnt(11)
	s_waitcnt lgkmcnt(0)
	s_barrier
	s_setprio 1
	s_waitcnt lgkmcnt(0)
	v_mfma_f32_16x16x32_bf16 v[62:65], v[140:143], v[172:175], v[62:65]
	v_mfma_f32_16x16x32_bf16 v[58:61], v[148:151], v[172:175], v[58:61]
	v_mfma_f32_16x16x32_bf16 v[46:49], v[140:143], v[180:183], v[46:49]
	v_mfma_f32_16x16x32_bf16 v[42:45], v[148:151], v[180:183], v[42:45]
	v_mfma_f32_16x16x32_bf16 v[28:31], v[140:143], v[188:191], v[28:31]
	v_mfma_f32_16x16x32_bf16 v[24:27], v[148:151], v[188:191], v[24:27]
	v_mfma_f32_16x16x32_bf16 v[12:15], v[140:143], v[202:205], v[12:15]
	v_mfma_f32_16x16x32_bf16 v[8:11], v[148:151], v[202:205], v[8:11]
	v_mfma_f32_16x16x32_bf16 v[62:65], v[144:147], v[176:179], v[62:65]
	v_mfma_f32_16x16x32_bf16 v[58:61], v[152:155], v[176:179], v[58:61]
	v_mfma_f32_16x16x32_bf16 v[46:49], v[144:147], v[184:187], v[46:49]
	v_mfma_f32_16x16x32_bf16 v[42:45], v[152:155], v[184:187], v[42:45]
	v_mfma_f32_16x16x32_bf16 v[28:31], v[144:147], v[198:201], v[28:31]
	v_mfma_f32_16x16x32_bf16 v[24:27], v[152:155], v[198:201], v[24:27]
	v_mfma_f32_16x16x32_bf16 v[12:15], v[144:147], v[206:209], v[12:15]
	v_mfma_f32_16x16x32_bf16 v[8:11], v[152:155], v[206:209], v[8:11]
	s_setprio 0
	s_setprio 1
	v_mfma_f32_16x16x32_bf16 v[54:57], v[156:159], v[172:175], v[54:57]
	v_mfma_f32_16x16x32_bf16 v[50:53], v[164:167], v[172:175], v[50:53]
	v_mfma_f32_16x16x32_bf16 v[38:41], v[156:159], v[180:183], v[38:41]
	v_mfma_f32_16x16x32_bf16 v[34:37], v[164:167], v[180:183], v[34:37]
	v_mfma_f32_16x16x32_bf16 v[20:23], v[156:159], v[188:191], v[20:23]
	v_mfma_f32_16x16x32_bf16 v[16:19], v[164:167], v[188:191], v[16:19]
	v_mfma_f32_16x16x32_bf16 v[4:7], v[156:159], v[202:205], v[4:7]
	v_mfma_f32_16x16x32_bf16 v[0:3], v[164:167], v[202:205], v[0:3]
	v_mfma_f32_16x16x32_bf16 v[54:57], v[160:163], v[176:179], v[54:57]
	v_mfma_f32_16x16x32_bf16 v[50:53], v[168:171], v[176:179], v[50:53]
	v_mfma_f32_16x16x32_bf16 v[38:41], v[160:163], v[184:187], v[38:41]
	v_mfma_f32_16x16x32_bf16 v[34:37], v[168:171], v[184:187], v[34:37]
	v_mfma_f32_16x16x32_bf16 v[20:23], v[160:163], v[198:201], v[20:23]
	v_mfma_f32_16x16x32_bf16 v[16:19], v[168:171], v[198:201], v[16:19]
	v_mfma_f32_16x16x32_bf16 v[4:7], v[160:163], v[206:209], v[4:7]
	v_mfma_f32_16x16x32_bf16 v[0:3], v[168:171], v[206:209], v[0:3]
	s_setprio 0
	s_barrier
	s_add_i32 s46, s46, 2
	s_add_u32 s26, s26, 0x100
	s_addc_u32 s27, s27, 0
	s_add_u32 s44, s44, 0x100
	s_addc_u32 s45, s45, 0
	s_mov_b32 s60, 1
	s_branch .LBB0_1057
; __device__ __forceinline__ unsigned cvt_pk_bf16(float lo, float hi) { const f32x2_t v = {lo, hi}; const bf16x2_t c = __builtin_convertvector(v, bf16x2_t); return __builtin_bit_cast(unsigned, c); }
; __device__ __forceinline__ float siluf_fast(float x) { return x * sigmoidf_fast(x); }
; #define PG8_BAR __builtin_amdgcn_s_barrier()
;     __device__ __forceinline__ void operator()(const f32x4 (&acc)[2][2][4][2], const Unit& u, int wr, int wc, int fr, int fq) const {
;         const int row0 = u.pm * BM + wr * 64 + fr, col0 = u.pn * HALF + wc * 32 + 8 * fq;
; #pragma unroll
;         for (int ai = 0; ai < 2; ++ai)
; #pragma unroll
;             for (int m = 0; m < 4; ++m) { const size_t r = (size_t)(row0 + ai * HALF + m * 16);
;                 const f32x4 g0 = acc[ai][0][m][0], u0 = acc[ai][0][m][1], g1 = acc[ai][1][m][0], u1 = acc[ai][1][m][1];
;                 u32x4 w; w.x = cvt_pk_bf16(siluf_fast(g0[0]) * u0[0], siluf_fast(g0[1]) * u0[1]); w.y = cvt_pk_bf16(siluf_fast(g0[2]) * u0[2], siluf_fast(g0[3]) * u0[3]);
;                 w.z = cvt_pk_bf16(siluf_fast(g1[0]) * u1[0], siluf_fast(g1[1]) * u1[1]); w.w = cvt_pk_bf16(siluf_fast(g1[2]) * u1[2], siluf_fast(g1[3]) * u1[3]);
;                 *(u32x4*)(O + r * ldo + col0) = w; }
; template <class Epi, class Sched, bool ALIGN_EPI = false, bool SP2 = false, bool KHOOK = false>
; __device__ __forceinline__ void gemm_phase(PG8_LAS unsigned char* lds, const Gemm g, const Sched& S, const Epi& E, const int tid_in) {
;     ...
;         if constexpr (ALIGN_EPI) { if (wr == 0) PG8_BAR; }
.Lg4_kexit:
	s_and_b64 vcc, exec, s[4:5]
	s_cbranch_vccz .LBB0_1066
	s_barrier
.LBB0_1066:
	v_mul_f32_e32 v141, 0xbfb8aa3b, v126
	v_exp_f32_e32 v141, v141
	v_lshl_add_u32 v140, s18, 8, v136
	v_lshl_or_b32 v142, s19, 7, v138
	v_readlane_b32 s18, v254, 28
	v_add_f32_e32 v141, 1.0, v141
	v_rcp_f32_e32 v144, v141
	v_mul_f32_e32 v141, 0xbfb8aa3b, v127
	v_exp_f32_e32 v141, v141
	v_readlane_b32 s19, v254, 29
	v_ashrrev_i32_e32 v143, 31, v142
	s_movk_i32 s11, 0x2c00
	v_add_f32_e32 v141, 1.0, v141
	v_rcp_f32_e32 v145, v141
	s_andn2_b64 vcc, exec, s[14:15]
	v_pk_mul_f32 v[126:127], v[126:127], v[144:145]
	s_nop 0
	v_pk_mul_f32 v[122:123], v[122:123], v[126:127]
	s_nop 0
	v_cvt_pk_bf16_f32 v122, v122, v123
	v_mul_f32_e32 v123, 0xbfb8aa3b, v128
	v_exp_f32_e32 v123, v123
	s_nop 0
	v_add_f32_e32 v123, 1.0, v123
	v_rcp_f32_e32 v126, v123
	v_mul_f32_e32 v123, 0xbfb8aa3b, v129
	v_exp_f32_e32 v123, v123
	s_nop 0
	v_add_f32_e32 v123, 1.0, v123
	v_rcp_f32_e32 v127, v123
	s_nop 0
	v_pk_mul_f32 v[126:127], v[128:129], v[126:127]
	s_nop 0
	v_pk_mul_f32 v[124:125], v[124:125], v[126:127]
	s_nop 0
	v_cvt_pk_bf16_f32 v123, v124, v125
	v_mul_f32_e32 v124, 0xbfb8aa3b, v118
	v_mul_f32_e32 v125, 0xbfb8aa3b, v119
	v_exp_f32_e32 v124, v124
	v_exp_f32_e32 v125, v125
	v_add_f32_e32 v124, 1.0, v124
	v_add_f32_e32 v125, 1.0, v125
	v_rcp_f32_e32 v124, v124
	v_rcp_f32_e32 v125, v125
	s_nop 0
	v_pk_mul_f32 v[118:119], v[118:119], v[124:125]
	s_nop 0
	v_pk_mul_f32 v[114:115], v[114:115], v[118:119]
	s_nop 0
	v_cvt_pk_bf16_f32 v124, v114, v115
	v_mul_f32_e32 v114, 0xbfb8aa3b, v120
	v_mul_f32_e32 v115, 0xbfb8aa3b, v121
	v_exp_f32_e32 v114, v114
	v_exp_f32_e32 v115, v115
	v_add_f32_e32 v114, 1.0, v114
	v_add_f32_e32 v115, 1.0, v115
	v_rcp_f32_e32 v114, v114
	v_rcp_f32_e32 v115, v115
	s_nop 0
	v_pk_mul_f32 v[114:115], v[120:121], v[114:115]
	s_nop 0
	v_pk_mul_f32 v[114:115], v[116:117], v[114:115]
	v_lshlrev_b64 v[116:117], 1, v[142:143]
	v_cvt_pk_bf16_f32 v125, v114, v115
	v_mov_b64_e32 v[114:115], s[18:19]
	v_mad_i64_i32 v[118:119], s[18:19], v140, s11, v[114:115]
	v_lshl_add_u64 v[118:119], v[118:119], 0, v[116:117]
	global_store_dwordx4 v[118:119], v[122:125], off
	v_mul_f32_e32 v118, 0xbfb8aa3b, v110
	v_mul_f32_e32 v119, 0xbfb8aa3b, v111
	v_exp_f32_e32 v118, v118
	v_exp_f32_e32 v119, v119
	v_or_b32_e32 v120, 16, v140
	v_add_f32_e32 v118, 1.0, v118
	v_add_f32_e32 v119, 1.0, v119
	v_rcp_f32_e32 v118, v118
	v_rcp_f32_e32 v119, v119
	s_nop 0
	v_pk_mul_f32 v[110:111], v[110:111], v[118:119]
	s_nop 0
	v_pk_mul_f32 v[106:107], v[106:107], v[110:111]
	s_nop 0
	v_cvt_pk_bf16_f32 v106, v106, v107
	v_mul_f32_e32 v107, 0xbfb8aa3b, v112
	v_exp_f32_e32 v107, v107
	s_nop 0
	v_add_f32_e32 v107, 1.0, v107
	v_rcp_f32_e32 v110, v107
	v_mul_f32_e32 v107, 0xbfb8aa3b, v113
	v_exp_f32_e32 v107, v107
	s_nop 0
	v_add_f32_e32 v107, 1.0, v107
	v_rcp_f32_e32 v111, v107
	s_nop 0
	v_pk_mul_f32 v[110:111], v[112:113], v[110:111]
	s_nop 0
	v_pk_mul_f32 v[108:109], v[108:109], v[110:111]
	s_nop 0
	v_cvt_pk_bf16_f32 v107, v108, v109
	v_mul_f32_e32 v108, 0xbfb8aa3b, v102
	v_mul_f32_e32 v109, 0xbfb8aa3b, v103
	v_exp_f32_e32 v108, v108
	v_exp_f32_e32 v109, v109
	v_add_f32_e32 v108, 1.0, v108
	v_add_f32_e32 v109, 1.0, v109
	v_rcp_f32_e32 v108, v108
	v_rcp_f32_e32 v109, v109
	s_nop 0
	v_pk_mul_f32 v[102:103], v[102:103], v[108:109]
	s_nop 0
	v_pk_mul_f32 v[98:99], v[98:99], v[102:103]
	s_nop 0
	v_cvt_pk_bf16_f32 v108, v98, v99
	v_mul_f32_e32 v98, 0xbfb8aa3b, v104
	v_mul_f32_e32 v99, 0xbfb8aa3b, v105
	v_exp_f32_e32 v98, v98
	v_exp_f32_e32 v99, v99
	v_add_f32_e32 v98, 1.0, v98
	v_add_f32_e32 v99, 1.0, v99
	v_rcp_f32_e32 v98, v98
	v_rcp_f32_e32 v99, v99
	s_nop 0
	v_pk_mul_f32 v[98:99], v[104:105], v[98:99]
	s_nop 0
	v_pk_mul_f32 v[98:99], v[100:101], v[98:99]
	v_or_b32_e32 v100, 32, v140
	v_cvt_pk_bf16_f32 v109, v98, v99
	v_mad_i64_i32 v[98:99], s[18:19], v120, s11, v[114:115]
	v_lshl_add_u64 v[98:99], v[98:99], 0, v[116:117]
	global_store_dwordx4 v[98:99], v[106:109], off
	v_mul_f32_e32 v98, 0xbfb8aa3b, v94
	v_mul_f32_e32 v99, 0xbfb8aa3b, v95
	v_exp_f32_e32 v98, v98
	v_exp_f32_e32 v99, v99
	v_add_f32_e32 v98, 1.0, v98
	v_add_f32_e32 v99, 1.0, v99
	v_rcp_f32_e32 v98, v98
	v_rcp_f32_e32 v99, v99
	s_nop 0
	v_pk_mul_f32 v[94:95], v[94:95], v[98:99]
	s_nop 0
	v_pk_mul_f32 v[90:91], v[90:91], v[94:95]
	s_nop 0
	v_cvt_pk_bf16_f32 v90, v90, v91
	v_mul_f32_e32 v91, 0xbfb8aa3b, v96
	v_exp_f32_e32 v91, v91
	s_nop 0
	v_add_f32_e32 v91, 1.0, v91
	v_rcp_f32_e32 v94, v91
	v_mul_f32_e32 v91, 0xbfb8aa3b, v97
	v_exp_f32_e32 v91, v91
	s_nop 0
	v_add_f32_e32 v91, 1.0, v91
	v_rcp_f32_e32 v95, v91
	s_nop 0
	v_pk_mul_f32 v[94:95], v[96:97], v[94:95]
	s_nop 0
	v_pk_mul_f32 v[92:93], v[92:93], v[94:95]
	s_nop 0
	v_cvt_pk_bf16_f32 v91, v92, v93
	v_mul_f32_e32 v92, 0xbfb8aa3b, v86
	v_mul_f32_e32 v93, 0xbfb8aa3b, v87
	v_exp_f32_e32 v92, v92
	v_exp_f32_e32 v93, v93
	v_add_f32_e32 v92, 1.0, v92
	v_add_f32_e32 v93, 1.0, v93
	v_rcp_f32_e32 v92, v92
	v_rcp_f32_e32 v93, v93
	s_nop 0
	v_pk_mul_f32 v[86:87], v[86:87], v[92:93]
	s_nop 0
	v_pk_mul_f32 v[82:83], v[82:83], v[86:87]
	s_nop 0
	v_cvt_pk_bf16_f32 v92, v82, v83
	v_mul_f32_e32 v82, 0xbfb8aa3b, v88
	v_mul_f32_e32 v83, 0xbfb8aa3b, v89
	v_exp_f32_e32 v82, v82
	v_exp_f32_e32 v83, v83
	v_add_f32_e32 v82, 1.0, v82
	v_add_f32_e32 v83, 1.0, v83
	v_rcp_f32_e32 v82, v82
	v_rcp_f32_e32 v83, v83
	s_nop 0
	v_pk_mul_f32 v[82:83], v[88:89], v[82:83]
	s_nop 0
	v_pk_mul_f32 v[82:83], v[84:85], v[82:83]
	v_or_b32_e32 v84, 48, v140
	v_cvt_pk_bf16_f32 v93, v82, v83
	v_mad_i64_i32 v[82:83], s[18:19], v100, s11, v[114:115]
	v_lshl_add_u64 v[82:83], v[82:83], 0, v[116:117]
	global_store_dwordx4 v[82:83], v[90:93], off
; __device__ __forceinline__ unsigned cvt_pk_bf16(float lo, float hi) { const f32x2_t v = {lo, hi}; const bf16x2_t c = __builtin_convertvector(v, bf16x2_t); return __builtin_bit_cast(unsigned, c); }
; __device__ __forceinline__ float siluf_fast(float x) { return x * sigmoidf_fast(x); }
;     __device__ __forceinline__ void operator()(const f32x4 (&acc)[2][2][4][2], const Unit& u, int wr, int wc, int fr, int fq) const {
;         const int row0 = u.pm * BM + wr * 64 + fr, col0 = u.pn * HALF + wc * 32 + 8 * fq;
; #pragma unroll
;         for (int ai = 0; ai < 2; ++ai)
; #pragma unroll
;             for (int m = 0; m < 4; ++m) { const size_t r = (size_t)(row0 + ai * HALF + m * 16);
;                 const f32x4 g0 = acc[ai][0][m][0], u0 = acc[ai][0][m][1], g1 = acc[ai][1][m][0], u1 = acc[ai][1][m][1];
;                 u32x4 w; w.x = cvt_pk_bf16(siluf_fast(g0[0]) * u0[0], siluf_fast(g0[1]) * u0[1]); w.y = cvt_pk_bf16(siluf_fast(g0[2]) * u0[2], siluf_fast(g0[3]) * u0[3]);
;                 w.z = cvt_pk_bf16(siluf_fast(g1[0]) * u1[0], siluf_fast(g1[1]) * u1[1]); w.w = cvt_pk_bf16(siluf_fast(g1[2]) * u1[2], siluf_fast(g1[3]) * u1[3]);
;                 *(u32x4*)(O + r * ldo + col0) = w; }
	v_mul_f32_e32 v82, 0xbfb8aa3b, v78
	v_mul_f32_e32 v83, 0xbfb8aa3b, v79
	v_exp_f32_e32 v82, v82
	v_exp_f32_e32 v83, v83
	v_add_f32_e32 v82, 1.0, v82
	v_add_f32_e32 v83, 1.0, v83
	v_rcp_f32_e32 v82, v82
	v_rcp_f32_e32 v83, v83
	s_nop 0
	v_pk_mul_f32 v[78:79], v[78:79], v[82:83]
	s_nop 0
	v_pk_mul_f32 v[74:75], v[74:75], v[78:79]
	s_nop 0
	v_cvt_pk_bf16_f32 v74, v74, v75
	v_mul_f32_e32 v75, 0xbfb8aa3b, v80
	v_exp_f32_e32 v75, v75
	s_nop 0
	v_add_f32_e32 v75, 1.0, v75
	v_rcp_f32_e32 v78, v75
	v_mul_f32_e32 v75, 0xbfb8aa3b, v81
	v_exp_f32_e32 v75, v75
	s_nop 0
	v_add_f32_e32 v75, 1.0, v75
	v_rcp_f32_e32 v79, v75
	s_nop 0
	v_pk_mul_f32 v[78:79], v[80:81], v[78:79]
	s_nop 0
	v_pk_mul_f32 v[76:77], v[76:77], v[78:79]
	s_nop 0
	v_cvt_pk_bf16_f32 v75, v76, v77
	v_mul_f32_e32 v76, 0xbfb8aa3b, v70
	v_mul_f32_e32 v77, 0xbfb8aa3b, v71
	v_exp_f32_e32 v76, v76
	v_exp_f32_e32 v77, v77
	v_add_f32_e32 v76, 1.0, v76
	v_add_f32_e32 v77, 1.0, v77
	v_rcp_f32_e32 v76, v76
	v_rcp_f32_e32 v77, v77
	s_nop 0
	v_pk_mul_f32 v[70:71], v[70:71], v[76:77]
	s_nop 0
	v_pk_mul_f32 v[66:67], v[66:67], v[70:71]
	s_nop 0
	v_cvt_pk_bf16_f32 v76, v66, v67
	v_mul_f32_e32 v66, 0xbfb8aa3b, v72
	v_mul_f32_e32 v67, 0xbfb8aa3b, v73
	v_exp_f32_e32 v66, v66
	v_exp_f32_e32 v67, v67
	v_add_f32_e32 v66, 1.0, v66
	v_add_f32_e32 v67, 1.0, v67
	v_rcp_f32_e32 v66, v66
	v_rcp_f32_e32 v67, v67
	s_nop 0
	v_pk_mul_f32 v[66:67], v[72:73], v[66:67]
	s_nop 0
	v_pk_mul_f32 v[66:67], v[68:69], v[66:67]
	v_add_u32_e32 v68, 0x80, v140
	v_cvt_pk_bf16_f32 v77, v66, v67
	v_mad_i64_i32 v[66:67], s[18:19], v84, s11, v[114:115]
	v_lshl_add_u64 v[66:67], v[66:67], 0, v[116:117]
	global_store_dwordx4 v[66:67], v[74:77], off
	v_mul_f32_e32 v66, 0xbfb8aa3b, v62
	v_mul_f32_e32 v67, 0xbfb8aa3b, v63
	v_exp_f32_e32 v66, v66
	v_exp_f32_e32 v67, v67
	v_add_f32_e32 v66, 1.0, v66
	v_add_f32_e32 v67, 1.0, v67
	v_rcp_f32_e32 v66, v66
	v_rcp_f32_e32 v67, v67
	s_nop 0
	v_pk_mul_f32 v[62:63], v[62:63], v[66:67]
	s_nop 0
	v_pk_mul_f32 v[58:59], v[58:59], v[62:63]
	s_nop 0
	v_cvt_pk_bf16_f32 v58, v58, v59
	v_mul_f32_e32 v59, 0xbfb8aa3b, v64
	v_exp_f32_e32 v59, v59
	s_nop 0
	v_add_f32_e32 v59, 1.0, v59
	v_rcp_f32_e32 v62, v59
	v_mul_f32_e32 v59, 0xbfb8aa3b, v65
	v_exp_f32_e32 v59, v59
	s_nop 0
	v_add_f32_e32 v59, 1.0, v59
	v_rcp_f32_e32 v63, v59
	s_nop 0
	v_pk_mul_f32 v[62:63], v[64:65], v[62:63]
	s_nop 0
	v_pk_mul_f32 v[60:61], v[60:61], v[62:63]
	s_nop 0
	v_cvt_pk_bf16_f32 v59, v60, v61
	v_mul_f32_e32 v60, 0xbfb8aa3b, v54
	v_mul_f32_e32 v61, 0xbfb8aa3b, v55
	v_exp_f32_e32 v60, v60
	v_exp_f32_e32 v61, v61
	v_add_f32_e32 v60, 1.0, v60
	v_add_f32_e32 v61, 1.0, v61
	v_rcp_f32_e32 v60, v60
	v_rcp_f32_e32 v61, v61
	s_nop 0
	v_pk_mul_f32 v[54:55], v[54:55], v[60:61]
	s_nop 0
	v_pk_mul_f32 v[50:51], v[50:51], v[54:55]
	s_nop 0
	v_cvt_pk_bf16_f32 v60, v50, v51
	v_mul_f32_e32 v50, 0xbfb8aa3b, v56
	v_mul_f32_e32 v51, 0xbfb8aa3b, v57
	v_exp_f32_e32 v50, v50
	v_exp_f32_e32 v51, v51
	v_add_f32_e32 v50, 1.0, v50
	v_add_f32_e32 v51, 1.0, v51
	v_rcp_f32_e32 v50, v50
	v_rcp_f32_e32 v51, v51
	s_nop 0
	v_pk_mul_f32 v[50:51], v[56:57], v[50:51]
	s_nop 0
	v_pk_mul_f32 v[50:51], v[52:53], v[50:51]
	v_add_u32_e32 v52, 0x90, v140
	v_cvt_pk_bf16_f32 v61, v50, v51
	v_mad_i64_i32 v[50:51], s[18:19], v68, s11, v[114:115]
	v_lshl_add_u64 v[50:51], v[50:51], 0, v[116:117]
	global_store_dwordx4 v[50:51], v[58:61], off
	v_mul_f32_e32 v50, 0xbfb8aa3b, v46
	v_mul_f32_e32 v51, 0xbfb8aa3b, v47
	v_exp_f32_e32 v50, v50
	v_exp_f32_e32 v51, v51
	v_add_f32_e32 v50, 1.0, v50
	v_add_f32_e32 v51, 1.0, v51
	v_rcp_f32_e32 v50, v50
	v_rcp_f32_e32 v51, v51
	s_nop 0
	v_pk_mul_f32 v[46:47], v[46:47], v[50:51]
	s_nop 0
	v_pk_mul_f32 v[42:43], v[42:43], v[46:47]
	s_nop 0
	v_cvt_pk_bf16_f32 v42, v42, v43
	v_mul_f32_e32 v43, 0xbfb8aa3b, v48
	v_exp_f32_e32 v43, v43
	s_nop 0
	v_add_f32_e32 v43, 1.0, v43
	v_rcp_f32_e32 v46, v43
	v_mul_f32_e32 v43, 0xbfb8aa3b, v49
	v_exp_f32_e32 v43, v43
	s_nop 0
	v_add_f32_e32 v43, 1.0, v43
	v_rcp_f32_e32 v47, v43
	s_nop 0
	v_pk_mul_f32 v[46:47], v[48:49], v[46:47]
	s_nop 0
	v_pk_mul_f32 v[44:45], v[44:45], v[46:47]
	s_nop 0
	v_cvt_pk_bf16_f32 v43, v44, v45
	v_mul_f32_e32 v44, 0xbfb8aa3b, v38
	v_mul_f32_e32 v45, 0xbfb8aa3b, v39
	v_exp_f32_e32 v44, v44
; __device__ __forceinline__ unsigned cvt_pk_bf16(float lo, float hi) { const f32x2_t v = {lo, hi}; const bf16x2_t c = __builtin_convertvector(v, bf16x2_t); return __builtin_bit_cast(unsigned, c); }
; __device__ __forceinline__ float siluf_fast(float x) { return x * sigmoidf_fast(x); }
; #define PG8_BAR __builtin_amdgcn_s_barrier()
;     __device__ __forceinline__ void operator()(const f32x4 (&acc)[2][2][4][2], const Unit& u, int wr, int wc, int fr, int fq) const {
;         const int row0 = u.pm * BM + wr * 64 + fr, col0 = u.pn * HALF + wc * 32 + 8 * fq;
; #pragma unroll
;         for (int ai = 0; ai < 2; ++ai)
; #pragma unroll
;             for (int m = 0; m < 4; ++m) { const size_t r = (size_t)(row0 + ai * HALF + m * 16);
;                 const f32x4 g0 = acc[ai][0][m][0], u0 = acc[ai][0][m][1], g1 = acc[ai][1][m][0], u1 = acc[ai][1][m][1];
;                 u32x4 w; w.x = cvt_pk_bf16(siluf_fast(g0[0]) * u0[0], siluf_fast(g0[1]) * u0[1]); w.y = cvt_pk_bf16(siluf_fast(g0[2]) * u0[2], siluf_fast(g0[3]) * u0[3]);
;                 w.z = cvt_pk_bf16(siluf_fast(g1[0]) * u1[0], siluf_fast(g1[1]) * u1[1]); w.w = cvt_pk_bf16(siluf_fast(g1[2]) * u1[2], siluf_fast(g1[3]) * u1[3]);
;                 *(u32x4*)(O + r * ldo + col0) = w; }
; template <class Epi, class Sched, bool ALIGN_EPI = false, bool SP2 = false, bool KHOOK = false>
; __device__ __forceinline__ void gemm_phase(PG8_LAS unsigned char* lds, const Gemm g, const Sched& S, const Epi& E, const int tid_in) {
;     ...
;         if (!has_next) break;
; #pragma unroll
;         for (int a = 0; a < 2; ++a)
; #pragma unroll
;             for (int b = 0; b < 2; ++b)
; #pragma unroll
;                 for (int m = 0; m < 4; ++m)
; #pragma unroll
;                     for (int n = 0; n < 2; ++n) acc[a][b][m][n] = (f32x4){0.f, 0.f, 0.f, 0.f};
;         cur = nxt; cA = nA; cB = nB; ++ui; load_rr(cur);
;         if constexpr (ALIGN_EPI) { if (wr == 1) PG8_BAR; }
	v_exp_f32_e32 v45, v45
	v_add_f32_e32 v44, 1.0, v44
	v_add_f32_e32 v45, 1.0, v45
	v_rcp_f32_e32 v44, v44
	v_rcp_f32_e32 v45, v45
	s_nop 0
	v_pk_mul_f32 v[38:39], v[38:39], v[44:45]
	s_nop 0
	v_pk_mul_f32 v[34:35], v[34:35], v[38:39]
	s_nop 0
	v_cvt_pk_bf16_f32 v44, v34, v35
	v_mul_f32_e32 v34, 0xbfb8aa3b, v40
	v_mul_f32_e32 v35, 0xbfb8aa3b, v41
	v_exp_f32_e32 v34, v34
	v_exp_f32_e32 v35, v35
	v_add_f32_e32 v34, 1.0, v34
	v_add_f32_e32 v35, 1.0, v35
	v_rcp_f32_e32 v34, v34
	v_rcp_f32_e32 v35, v35
	s_nop 0
	v_pk_mul_f32 v[34:35], v[40:41], v[34:35]
	s_nop 0
	v_pk_mul_f32 v[34:35], v[36:37], v[34:35]
	v_add_u32_e32 v36, 0xa0, v140
	v_cvt_pk_bf16_f32 v45, v34, v35
	v_mad_i64_i32 v[34:35], s[18:19], v52, s11, v[114:115]
	v_lshl_add_u64 v[34:35], v[34:35], 0, v[116:117]
	global_store_dwordx4 v[34:35], v[42:45], off
	v_mul_f32_e32 v34, 0xbfb8aa3b, v28
	v_mul_f32_e32 v35, 0xbfb8aa3b, v29
	v_exp_f32_e32 v34, v34
	v_exp_f32_e32 v35, v35
	v_add_f32_e32 v34, 1.0, v34
	v_add_f32_e32 v35, 1.0, v35
	v_rcp_f32_e32 v34, v34
	v_rcp_f32_e32 v35, v35
	s_nop 0
	v_pk_mul_f32 v[28:29], v[28:29], v[34:35]
	s_nop 0
	v_pk_mul_f32 v[24:25], v[24:25], v[28:29]
	s_nop 0
	v_cvt_pk_bf16_f32 v24, v24, v25
	v_mul_f32_e32 v25, 0xbfb8aa3b, v30
	v_exp_f32_e32 v25, v25
	s_nop 0
	v_add_f32_e32 v25, 1.0, v25
	v_rcp_f32_e32 v28, v25
	v_mul_f32_e32 v25, 0xbfb8aa3b, v31
	v_exp_f32_e32 v25, v25
	s_nop 0
	v_add_f32_e32 v25, 1.0, v25
	v_rcp_f32_e32 v29, v25
	s_nop 0
	v_pk_mul_f32 v[28:29], v[30:31], v[28:29]
	s_nop 0
	v_pk_mul_f32 v[26:27], v[26:27], v[28:29]
	s_nop 0
	v_cvt_pk_bf16_f32 v25, v26, v27
	v_mul_f32_e32 v26, 0xbfb8aa3b, v20
	v_mul_f32_e32 v27, 0xbfb8aa3b, v21
	v_exp_f32_e32 v26, v26
	v_exp_f32_e32 v27, v27
	v_add_f32_e32 v26, 1.0, v26
	v_add_f32_e32 v27, 1.0, v27
	v_rcp_f32_e32 v26, v26
	v_rcp_f32_e32 v27, v27
	s_nop 0
	v_pk_mul_f32 v[20:21], v[20:21], v[26:27]
	s_nop 0
	v_pk_mul_f32 v[16:17], v[16:17], v[20:21]
	s_nop 0
	v_cvt_pk_bf16_f32 v26, v16, v17
	v_mul_f32_e32 v16, 0xbfb8aa3b, v22
	v_mul_f32_e32 v17, 0xbfb8aa3b, v23
	v_exp_f32_e32 v16, v16
	v_exp_f32_e32 v17, v17
	v_add_f32_e32 v16, 1.0, v16
	v_add_f32_e32 v17, 1.0, v17
	v_rcp_f32_e32 v16, v16
	v_rcp_f32_e32 v17, v17
	s_nop 0
	v_pk_mul_f32 v[16:17], v[22:23], v[16:17]
	s_nop 0
	v_pk_mul_f32 v[16:17], v[18:19], v[16:17]
	v_add_u32_e32 v18, 0xb0, v140
	v_cvt_pk_bf16_f32 v27, v16, v17
	v_mad_i64_i32 v[16:17], s[18:19], v36, s11, v[114:115]
	v_lshl_add_u64 v[16:17], v[16:17], 0, v[116:117]
	global_store_dwordx4 v[16:17], v[24:27], off
	v_mul_f32_e32 v16, 0xbfb8aa3b, v12
	v_mul_f32_e32 v17, 0xbfb8aa3b, v13
	v_exp_f32_e32 v16, v16
	v_exp_f32_e32 v17, v17
	v_add_f32_e32 v16, 1.0, v16
	v_add_f32_e32 v17, 1.0, v17
	v_rcp_f32_e32 v16, v16
	v_rcp_f32_e32 v17, v17
	s_nop 0
	v_pk_mul_f32 v[12:13], v[12:13], v[16:17]
	s_nop 0
	v_pk_mul_f32 v[8:9], v[8:9], v[12:13]
	s_nop 0
	v_cvt_pk_bf16_f32 v8, v8, v9
	v_mul_f32_e32 v9, 0xbfb8aa3b, v14
	v_exp_f32_e32 v9, v9
	s_nop 0
	v_add_f32_e32 v9, 1.0, v9
	v_rcp_f32_e32 v12, v9
	v_mul_f32_e32 v9, 0xbfb8aa3b, v15
	v_exp_f32_e32 v9, v9
	s_nop 0
	v_add_f32_e32 v9, 1.0, v9
	v_rcp_f32_e32 v13, v9
	s_nop 0
	v_pk_mul_f32 v[12:13], v[14:15], v[12:13]
	s_nop 0
	v_pk_mul_f32 v[10:11], v[10:11], v[12:13]
	s_nop 0
	v_cvt_pk_bf16_f32 v9, v10, v11
	v_mul_f32_e32 v10, 0xbfb8aa3b, v4
	v_mul_f32_e32 v11, 0xbfb8aa3b, v5
	v_exp_f32_e32 v10, v10
	v_exp_f32_e32 v11, v11
	v_add_f32_e32 v10, 1.0, v10
	v_add_f32_e32 v11, 1.0, v11
	v_rcp_f32_e32 v10, v10
	v_rcp_f32_e32 v11, v11
	s_nop 0
	v_pk_mul_f32 v[4:5], v[4:5], v[10:11]
	s_nop 0
	v_pk_mul_f32 v[0:1], v[0:1], v[4:5]
	s_nop 0
	v_cvt_pk_bf16_f32 v10, v0, v1
	v_mul_f32_e32 v0, 0xbfb8aa3b, v6
	v_mul_f32_e32 v1, 0xbfb8aa3b, v7
	v_exp_f32_e32 v0, v0
	v_exp_f32_e32 v1, v1
	v_add_f32_e32 v0, 1.0, v0
	v_add_f32_e32 v1, 1.0, v1
	v_rcp_f32_e32 v0, v0
	v_rcp_f32_e32 v1, v1
	s_nop 0
	v_pk_mul_f32 v[0:1], v[6:7], v[0:1]
	s_nop 0
	v_pk_mul_f32 v[0:1], v[2:3], v[0:1]
	s_nop 0
	v_cvt_pk_bf16_f32 v11, v0, v1
	v_mad_i64_i32 v[0:1], s[18:19], v18, s11, v[114:115]
	v_lshl_add_u64 v[0:1], v[0:1], 0, v[116:117]
	s_mov_b64 s[18:19], -1
	global_store_dwordx4 v[0:1], v[8:11], off
	s_cbranch_vccnz .LBB0_1058
	s_andn2_b64 vcc, exec, s[0:1]
	s_cbranch_vccnz .LBB0_1057
	s_barrier
	s_branch .LBB0_1057
